# weight-conversion prologue rewritten as one generic hand-written routine with 16-byte row loads
# speedup vs baseline: 1.1292x; 1.0335x over previous
; __device__ __forceinline__ void transpose_item(const float* W, int K, int N, bf16_t* WT, int mode, const float* gain, LAS float* scr, int item, int lane) {
;     const int nblk = (N + 31) / 32, kb = item / nblk, nb = item % nblk, k0 = 64 * kb, n0 = 32 * nb;
; __device__ __forceinline__ void prologue(LAS unsigned char* lds, int wave, int lane, int gw, int NGW) {
;     ...
;     for (int it = gw; it < DEPTH * IT_LAYER; it += NGW) {
;         const int l = it / IT_LAYER; int r = it % IT_LAYER;
;         if (r < IT_WIN) { transpose_item(Ap->in[5] + (size_t)l * DM * NIN, DM, NIN, (bf16_t*)(ws + WS_WIN) + (size_t)l * NINP * DM, 4, Ap->in[2] + l * DM, scr, r, lane); continue; } r -= IT_WIN;
;         if (r < IT_GLU) { transpose_item(Ap->in[14] + (size_t)l * DSSM * 2 * DSSM, DSSM, 2 * DSSM, (bf16_t*)(ws + WS_WGLU) + (size_t)l * 2 * DSSM * DSSM, 1, nullptr, scr, r, lane); continue; } r -= IT_GLU;
;         if (r < IT_OUT) { transpose_item(Ap->in[22] + (size_t)l * DM * DM, DM, DM, (bf16_t*)(ws + WS_WOUT) + (size_t)l * DM * DM, 5, nullptr, scr, r, lane); continue; } r -= IT_OUT;
;         if (r < IT_G) { transpose_item(Ap->in[23] + (size_t)l * DM * DFF, DM, DFF, (bf16_t*)(ws + WS_WGU) + (size_t)l * 2 * DFF * DM, 2, Ap->in[3] + l * DM, scr, r, lane); continue; } r -= IT_G;
;         if (r < IT_U) { transpose_item(Ap->in[24] + (size_t)l * DM * DFF, DM, DFF, (bf16_t*)(ws + WS_WGU) + (size_t)l * 2 * DFF * DM, 3, Ap->in[3] + l * DM, scr, r, lane); continue; } r -= IT_U;
;         if (r < IT_D) { transpose_item(Ap->in[25] + (size_t)l * DFF * DM, DFF, DM, (bf16_t*)(ws + WS_WDN) + (size_t)l * DM * DFF, 5, nullptr, scr, r, lane); continue; } r -= IT_D;
;         if (r < IT_C1) { transpose_item(Ap->in[17] + (size_t)l * 2048 * 128, 2048, 128, (bf16_t*)(ws + WS_CW1) + (size_t)(l * 2 + 0) * 128 * 2048, 0, nullptr, scr, r, lane); continue; } r -= IT_C1;
;         if (r < IT_C1) { transpose_item(Ap->in[20] + (size_t)l * 2048 * 128, 2048, 128, (bf16_t*)(ws + WS_CW1) + (size_t)(l * 2 + 1) * 128 * 2048, 0, nullptr, scr, r, lane); continue; } r -= IT_C1;
;         if (r < IT_C2) { transpose_item(Ap->in[18] + (size_t)l * 128 * 64, 128, 64, (bf16_t*)(ws + WS_CW2) + (size_t)(l * 2 + 0) * 64 * 128, 0, nullptr, scr, r, lane); continue; } r -= IT_C2;
;         transpose_item(Ap->in[21] + (size_t)l * 128 * 64, 128, 64, (bf16_t*)(ws + WS_CW2) + (size_t)(l * 2 + 1) * 64 * 128, 0, nullptr, scr, r, lane);
.LBB0_2:
	s_or_b64 exec, exec, s[0:1]
	s_mov_b64 s[14:15], s[68:69]
	s_load_dwordx2 s[8:9], s[14:15], 0xd8
	s_ashr_i32 s0, s3, 6
	s_lshl_b32 s1, s4, 3
	s_add_i32 s10, s1, s0
	s_lshl_b32 s12, s2, 3
	s_cmp_gt_i32 s10, 0x1751f
	v_and_b32_e32 v12, 63, v3
	s_cbranch_scc1 .LBB0_331
	s_load_dwordx4 s[28:31], s[14:15], 0x10
	s_load_dwordx2 s[32:33], s[14:15], 0x28
	s_load_dwordx2 s[34:35], s[14:15], 0x70
	s_load_dwordx4 s[36:39], s[14:15], 0x88
	s_load_dwordx4 s[40:43], s[14:15], 0xa0
	s_load_dwordx8 s[44:51], s[14:15], 0xb0
	v_lshrrev_b32_e32 v20, 3, v12
	v_and_b32_e32 v21, 7, v12
	s_lshl_b32 s0, s77, 14
	v_lshlrev_b32_e32 v22, 4, v21
	v_lshlrev_b32_e32 v23, 2, v20
	v_mul_u32_u24_e32 v24, 0x84, v20
	v_mul_u32_u24_e32 v25, 0x420, v21
	v_add3_u32 v24, v24, v22, s0
	v_add3_u32 v25, v25, v23, s0
	v_bfe_u32 v26, v20, 2, 1
	v_and_b32_e32 v27, 3, v20
	v_lshl_or_b32 v28, v26, 4, v27
	v_lshl_or_b32 v29, v26, 7, v27
	s_mov_b32 s16, s10
	s_waitcnt lgkmcnt(0)
.Lpro_loop:
	s_cmp_ge_u32 s16, 23880
	s_cselect_b32 s17, 1, 0
	s_cmp_ge_u32 s16, 47760
	s_cselect_b32 s19, 1, 0
	s_add_u32 s17, s17, s19
	s_cmp_ge_u32 s16, 71640
	s_cselect_b32 s19, 1, 0
	s_add_u32 s17, s17, s19
	s_mul_i32 s19, s17, 23880
	s_sub_u32 s18, s16, s19
	s_cmp_lt_u32 s18, 3648
	s_cbranch_scc1 .Lpro_t0
	s_cmp_lt_u32 s18, 4672
	s_cbranch_scc1 .Lpro_t1
	s_cmp_lt_u32 s18, 6720
	s_cbranch_scc1 .Lpro_t2
	s_cmp_lt_u32 s18, 12352
	s_cbranch_scc1 .Lpro_t3
	s_cmp_lt_u32 s18, 17984
	s_cbranch_scc1 .Lpro_t4
	s_cmp_lt_u32 s18, 23616
	s_cbranch_scc1 .Lpro_t5
	s_cmp_lt_u32 s18, 23744
	s_cbranch_scc1 .Lpro_t6
	s_cmp_lt_u32 s18, 23872
	s_cbranch_scc1 .Lpro_t7
	s_cmp_lt_u32 s18, 23876
	s_cbranch_scc1 .Lpro_t8
	s_sub_u32 s19, s18, 23876
	s_lshr_b32 s23, s19, 1
	s_and_b32 s22, s19, 1
	s_lshl_b32 s23, s23, 6
	s_lshl_b32 s22, s22, 5
	s_mov_b32 s20, 256
	s_mov_b32 s21, 256
	s_mov_b32 s11, 0
	s_mov_b32 s13, 64
	s_mul_i32 s0, s17, 32768
	s_mul_hi_u32 s1, s17, 32768
	s_add_u32 s2, s42, s0
	s_addc_u32 s3, s43, s1
	s_mul_i32 s0, s23, 64
	s_add_u32 s0, s0, s22
	s_lshl_b32 s0, s0, 2
	s_add_u32 s2, s2, s0
	s_addc_u32 s3, s3, 0
	s_mul_i32 s0, s17, 32768
	s_mul_hi_u32 s1, s17, 32768
	s_add_u32 s0, s0, 395329536
	s_addc_u32 s1, s1, 0
	s_add_u32 s4, s8, s0
	s_addc_u32 s5, s9, s1
	s_mov_b32 s54, 0
	s_branch .Lpro_body
.Lpro_t8:
	s_sub_u32 s19, s18, 23872
	s_lshr_b32 s23, s19, 1
	s_and_b32 s22, s19, 1
	s_lshl_b32 s23, s23, 6
	s_lshl_b32 s22, s22, 5
	s_mov_b32 s20, 256
	s_mov_b32 s21, 256
	s_mov_b32 s11, 0
	s_mov_b32 s13, 64
	s_mul_i32 s0, s17, 32768
	s_mul_hi_u32 s1, s17, 32768
	s_add_u32 s2, s38, s0
	s_addc_u32 s3, s39, s1
	s_mul_i32 s0, s23, 64
	s_add_u32 s0, s0, s22
	s_lshl_b32 s0, s0, 2
	s_add_u32 s2, s2, s0
	s_addc_u32 s3, s3, 0
	s_mul_i32 s0, s17, 32768
	s_mul_hi_u32 s1, s17, 32768
	s_add_u32 s0, s0, 395313152
	s_addc_u32 s1, s1, 0
	s_add_u32 s4, s8, s0
	s_addc_u32 s5, s9, s1
	s_mov_b32 s54, 0
	s_branch .Lpro_body
.Lpro_t7:
	s_sub_u32 s19, s18, 23744
	s_lshr_b32 s23, s19, 2
	s_and_b32 s22, s19, 3
	s_lshl_b32 s23, s23, 6
	s_lshl_b32 s22, s22, 5
	s_mov_b32 s20, 4096
	s_mov_b32 s21, 512
	s_mov_b32 s11, 0
	s_mov_b32 s13, 128
	s_mul_i32 s0, s17, 1048576
	s_mul_hi_u32 s1, s17, 1048576
	s_add_u32 s2, s40, s0
	s_addc_u32 s3, s41, s1
	s_mul_i32 s0, s23, 128
	s_add_u32 s0, s0, s22
	s_lshl_b32 s0, s0, 2
	s_add_u32 s2, s2, s0
	s_addc_u32 s3, s3, 0
	s_mul_i32 s0, s17, 1048576
	s_mul_hi_u32 s1, s17, 1048576
	s_add_u32 s0, s0, 391643136
	s_addc_u32 s1, s1, 0
	s_add_u32 s4, s8, s0
	s_addc_u32 s5, s9, s1
	s_mov_b32 s54, 0
	s_branch .Lpro_body
.Lpro_t6:
	s_sub_u32 s19, s18, 23616
	s_lshr_b32 s23, s19, 2
	s_and_b32 s22, s19, 3
	s_lshl_b32 s23, s23, 6
	s_lshl_b32 s22, s22, 5
	s_mov_b32 s20, 4096
	s_mov_b32 s21, 512
	s_mov_b32 s11, 0
	s_mov_b32 s13, 128
	s_mul_i32 s0, s17, 1048576
	s_mul_hi_u32 s1, s17, 1048576
	s_add_u32 s2, s36, s0
	s_addc_u32 s3, s37, s1
	s_mul_i32 s0, s23, 128
	s_add_u32 s0, s0, s22
	s_lshl_b32 s0, s0, 2
	s_add_u32 s2, s2, s0
	s_addc_u32 s3, s3, 0
	s_mul_i32 s0, s17, 1048576
	s_mul_hi_u32 s1, s17, 1048576
	s_add_u32 s0, s0, 391118848
	s_addc_u32 s1, s1, 0
	s_add_u32 s4, s8, s0
	s_addc_u32 s5, s9, s1
	s_mov_b32 s54, 0
	s_branch .Lpro_body
.Lpro_t5:
	s_sub_u32 s19, s18, 17984
	s_lshr_b32 s23, s19, 6
	s_and_b32 s22, s19, 63
	s_lshl_b32 s23, s23, 6
	s_lshl_b32 s22, s22, 5
	s_mov_b32 s20, 11264
	s_mov_b32 s21, 8192
	s_mov_b32 s11, 5
	s_mov_b32 s13, 2048
	s_mul_i32 s0, s17, 46137344
	s_mul_hi_u32 s1, s17, 46137344
	s_add_u32 s2, s50, s0
	s_addc_u32 s3, s51, s1
	s_mul_i32 s0, s23, 2048
	s_add_u32 s0, s0, s22
	s_lshl_b32 s0, s0, 2
	s_add_u32 s2, s2, s0
	s_addc_u32 s3, s3, 0
	s_mul_i32 s0, s17, 23068672
	s_mul_hi_u32 s1, s17, 23068672
	s_add_u32 s0, s0, 298844160
	s_addc_u32 s1, s1, 0
	s_add_u32 s4, s8, s0
	s_addc_u32 s5, s9, s1
	s_mov_b32 s54, 0
	s_branch .Lpro_body
.Lpro_t4:
	s_sub_u32 s19, s18, 12352
	s_mul_i32 s23, s19, 23832
	s_lshr_b32 s23, s23, 22
	s_mul_i32 s22, s23, 176
	s_sub_u32 s22, s19, s22
	s_lshl_b32 s23, s23, 6
	s_lshl_b32 s22, s22, 5
	s_mov_b32 s20, 4096
	s_mov_b32 s21, 22528
	s_mov_b32 s11, 3
	s_mov_b32 s13, 5632
	s_mul_i32 s0, s17, 46137344
	s_mul_hi_u32 s1, s17, 46137344
	s_add_u32 s2, s48, s0
	s_addc_u32 s3, s49, s1
	s_mul_i32 s0, s23, 5632
	s_add_u32 s0, s0, s22
	s_lshl_b32 s0, s0, 2
	s_add_u32 s2, s2, s0
	s_addc_u32 s3, s3, 0
	s_mul_i32 s0, s17, 46137344
	s_mul_hi_u32 s1, s17, 46137344
	s_add_u32 s0, s0, 114294784
	s_addc_u32 s1, s1, 0
	s_add_u32 s4, s8, s0
	s_addc_u32 s5, s9, s1
	s_lshl_b32 s0, s17, 13
	s_lshl_b32 s1, s23, 2
	s_add_u32 s0, s0, s1
	s_add_u32 s52, s30, s0
	s_addc_u32 s53, s31, 0
	s_mov_b32 s54, 1
	s_branch .Lpro_body
; #define LAS __attribute__((address_space(3)))
; __device__ __forceinline__ void transpose_item(const float* W, int K, int N, bf16_t* WT, int mode, const float* gain, LAS float* scr, int item, int lane) {
;     const int nblk = (N + 31) / 32, kb = item / nblk, nb = item % nblk, k0 = 64 * kb, n0 = 32 * nb;
;     const int nn = n0 + (lane & 31);
;     float cs = 1.f; if (mode == 4 && nn >= C_Q && nn < C_KC) cs = 0.125f;
; #pragma unroll
;     for (int i = 0; i < 32; ++i) { const int kk = 2 * i + (lane >> 5);
;         float v = (nn < N) ? __builtin_nontemporal_load(&W[(size_t)(k0 + kk) * N + nn]) : 0.f;
; __device__ __forceinline__ void prologue(LAS unsigned char* lds, int wave, int lane, int gw, int NGW) {
;     ...
;         if (r < IT_WIN) { transpose_item(Ap->in[5] + (size_t)l * DM * NIN, DM, NIN, (bf16_t*)(ws + WS_WIN) + (size_t)l * NINP * DM, 4, Ap->in[2] + l * DM, scr, r, lane); continue; } r -= IT_WIN;
;         if (r < IT_GLU) { transpose_item(Ap->in[14] + (size_t)l * DSSM * 2 * DSSM, DSSM, 2 * DSSM, (bf16_t*)(ws + WS_WGLU) + (size_t)l * 2 * DSSM * DSSM, 1, nullptr, scr, r, lane); continue; } r -= IT_GLU;
;         if (r < IT_OUT) { transpose_item(Ap->in[22] + (size_t)l * DM * DM, DM, DM, (bf16_t*)(ws + WS_WOUT) + (size_t)l * DM * DM, 5, nullptr, scr, r, lane); continue; } r -= IT_OUT;
;         if (r < IT_G) { transpose_item(Ap->in[23] + (size_t)l * DM * DFF, DM, DFF, (bf16_t*)(ws + WS_WGU) + (size_t)l * 2 * DFF * DM, 2, Ap->in[3] + l * DM, scr, r, lane); continue; } r -= IT_G;
;         if (r < IT_U) { transpose_item(Ap->in[24] + (size_t)l * DM * DFF, DM, DFF, (bf16_t*)(ws + WS_WGU) + (size_t)l * 2 * DFF * DM, 3, Ap->in[3] + l * DM, scr, r, lane); continue; } r -= IT_U;
.Lpro_t3:
	s_sub_u32 s19, s18, 6720
	s_mul_i32 s23, s19, 23832
	s_lshr_b32 s23, s23, 22
	s_mul_i32 s22, s23, 176
	s_sub_u32 s22, s19, s22
	s_lshl_b32 s23, s23, 6
	s_lshl_b32 s22, s22, 5
	s_mov_b32 s20, 4096
	s_mov_b32 s21, 22528
	s_mov_b32 s11, 2
	s_mov_b32 s13, 5632
	s_mul_i32 s0, s17, 46137344
	s_mul_hi_u32 s1, s17, 46137344
	s_add_u32 s2, s46, s0
	s_addc_u32 s3, s47, s1
	s_mul_i32 s0, s23, 5632
	s_add_u32 s0, s0, s22
	s_lshl_b32 s0, s0, 2
	s_add_u32 s2, s2, s0
	s_addc_u32 s3, s3, 0
	s_mul_i32 s0, s17, 46137344
	s_mul_hi_u32 s1, s17, 46137344
	s_add_u32 s0, s0, 114294784
	s_addc_u32 s1, s1, 0
	s_add_u32 s4, s8, s0
	s_addc_u32 s5, s9, s1
	s_lshl_b32 s0, s17, 13
	s_lshl_b32 s1, s23, 2
	s_add_u32 s0, s0, s1
	s_add_u32 s52, s30, s0
	s_addc_u32 s53, s31, 0
	s_mov_b32 s54, 1
	s_branch .Lpro_body
.Lpro_t2:
	s_sub_u32 s19, s18, 4672
	s_lshr_b32 s23, s19, 6
	s_and_b32 s22, s19, 63
	s_lshl_b32 s23, s23, 6
	s_lshl_b32 s22, s22, 5
	s_mov_b32 s20, 4096
	s_mov_b32 s21, 8192
	s_mov_b32 s11, 5
	s_mov_b32 s13, 2048
	s_mul_i32 s0, s17, 16777216
	s_mul_hi_u32 s1, s17, 16777216
	s_add_u32 s2, s44, s0
	s_addc_u32 s3, s45, s1
	s_mul_i32 s0, s23, 2048
	s_add_u32 s0, s0, s22
	s_lshl_b32 s0, s0, 2
	s_add_u32 s2, s2, s0
	s_addc_u32 s3, s3, 0
	s_mul_i32 s0, s17, 8388608
	s_mul_hi_u32 s1, s17, 8388608
	s_add_u32 s0, s0, 80740352
	s_addc_u32 s1, s1, 0
	s_add_u32 s4, s8, s0
	s_addc_u32 s5, s9, s1
	s_mov_b32 s54, 0
	s_branch .Lpro_body
.Lpro_t1:
	s_sub_u32 s19, s18, 3648
	s_lshr_b32 s23, s19, 6
	s_and_b32 s22, s19, 63
	s_lshl_b32 s23, s23, 6
	s_lshl_b32 s22, s22, 5
	s_mov_b32 s20, 2048
	s_mov_b32 s21, 8192
	s_mov_b32 s11, 1
	s_mov_b32 s13, 2048
	s_mul_i32 s0, s17, 8388608
	s_mul_hi_u32 s1, s17, 8388608
	s_add_u32 s2, s34, s0
	s_addc_u32 s3, s35, s1
	s_mul_i32 s0, s23, 2048
	s_add_u32 s0, s0, s22
	s_lshl_b32 s0, s0, 2
	s_add_u32 s2, s2, s0
	s_addc_u32 s3, s3, 0
	s_mul_i32 s0, s17, 4194304
	s_mul_hi_u32 s1, s17, 4194304
	s_add_u32 s0, s0, 63963136
	s_addc_u32 s1, s1, 0
	s_add_u32 s4, s8, s0
	s_addc_u32 s5, s9, s1
	s_mov_b32 s54, 0
	s_branch .Lpro_body
.Lpro_t0:
	s_sub_u32 s19, s18, 0
	s_mul_i32 s23, s19, 36793
	s_lshr_b32 s23, s23, 22
	s_mul_i32 s22, s23, 114
	s_sub_u32 s22, s19, s22
	s_lshl_b32 s23, s23, 6
	s_lshl_b32 s22, s22, 5
	s_mov_b32 s20, 4096
	s_mov_b32 s21, 14528
	s_mov_b32 s11, 4
	s_mov_b32 s13, 3632
	s_mul_i32 s0, s17, 29753344
	s_mul_hi_u32 s1, s17, 29753344
	s_add_u32 s2, s32, s0
	s_addc_u32 s3, s33, s1
	s_mul_i32 s0, s23, 3632
	s_add_u32 s0, s0, s22
	s_lshl_b32 s0, s0, 2
	s_add_u32 s2, s2, s0
	s_addc_u32 s3, s3, 0
	s_mul_i32 s0, s17, 15728640
	s_mul_hi_u32 s1, s17, 15728640
	s_add_u32 s0, s0, 1048576
	s_addc_u32 s1, s1, 0
	s_add_u32 s4, s8, s0
	s_addc_u32 s5, s9, s1
	s_lshl_b32 s0, s17, 13
	s_lshl_b32 s1, s23, 2
	s_add_u32 s0, s0, s1
	s_add_u32 s52, s28, s0
	s_addc_u32 s53, s29, 0
	s_mov_b32 s54, 1
.Lpro_body:
	v_mul_lo_u32 v30, v20, s21
	s_sub_u32 s0, s13, s22
	s_lshr_b32 s0, s0, 2
	s_min_u32 s0, s0, 8
	v_add_u32_e32 v30, v30, v22
	s_lshl_b32 s1, s21, 3
	s_cmp_lt_u32 s0, 8
	s_cbranch_scc0 .Lpro_full
	v_mov_b32_e32 v32, 0
	v_mov_b32_e32 v33, 0
	v_mov_b32_e32 v34, 0
	v_mov_b32_e32 v35, 0
	v_mov_b32_e32 v36, 0
	v_mov_b32_e32 v37, 0
	v_mov_b32_e32 v38, 0
	v_mov_b32_e32 v39, 0
	v_mov_b32_e32 v40, 0
	v_mov_b32_e32 v41, 0
	v_mov_b32_e32 v42, 0
	v_mov_b32_e32 v43, 0
	v_mov_b32_e32 v44, 0
	v_mov_b32_e32 v45, 0
	v_mov_b32_e32 v46, 0
	v_mov_b32_e32 v47, 0
	v_mov_b32_e32 v48, 0
	v_mov_b32_e32 v49, 0
	v_mov_b32_e32 v50, 0
	v_mov_b32_e32 v51, 0
	v_mov_b32_e32 v52, 0
	v_mov_b32_e32 v53, 0
	v_mov_b32_e32 v54, 0
	v_mov_b32_e32 v55, 0
	v_mov_b32_e32 v56, 0
	v_mov_b32_e32 v57, 0
	v_mov_b32_e32 v58, 0
	v_mov_b32_e32 v59, 0
	v_mov_b32_e32 v60, 0
	v_mov_b32_e32 v61, 0
	v_mov_b32_e32 v62, 0
	v_mov_b32_e32 v63, 0
	v_cmp_gt_u32_e32 vcc, s0, v21
	s_and_saveexec_b64 s[56:57], vcc
	global_load_dwordx4 v[32:35], v30, s[2:3] nt
	s_add_u32 s2, s2, s1
	s_addc_u32 s3, s3, 0
	global_load_dwordx4 v[36:39], v30, s[2:3] nt
	s_add_u32 s2, s2, s1
	s_addc_u32 s3, s3, 0
	global_load_dwordx4 v[40:43], v30, s[2:3] nt
	s_add_u32 s2, s2, s1
	s_addc_u32 s3, s3, 0
	global_load_dwordx4 v[44:47], v30, s[2:3] nt
	s_add_u32 s2, s2, s1
	s_addc_u32 s3, s3, 0
	global_load_dwordx4 v[48:51], v30, s[2:3] nt
	s_add_u32 s2, s2, s1
	s_addc_u32 s3, s3, 0
	global_load_dwordx4 v[52:55], v30, s[2:3] nt
	s_add_u32 s2, s2, s1
	s_addc_u32 s3, s3, 0
	global_load_dwordx4 v[56:59], v30, s[2:3] nt
	s_add_u32 s2, s2, s1
	s_addc_u32 s3, s3, 0
	global_load_dwordx4 v[60:63], v30, s[2:3] nt
	s_mov_b64 exec, s[56:57]
	s_branch .Lpro_loaded
.Lpro_full:
	global_load_dwordx4 v[32:35], v30, s[2:3] nt
	s_add_u32 s2, s2, s1
	s_addc_u32 s3, s3, 0
	global_load_dwordx4 v[36:39], v30, s[2:3] nt
	s_add_u32 s2, s2, s1
	s_addc_u32 s3, s3, 0
	global_load_dwordx4 v[40:43], v30, s[2:3] nt
	s_add_u32 s2, s2, s1
	s_addc_u32 s3, s3, 0
	global_load_dwordx4 v[44:47], v30, s[2:3] nt
	s_add_u32 s2, s2, s1
	s_addc_u32 s3, s3, 0
	global_load_dwordx4 v[48:51], v30, s[2:3] nt
	s_add_u32 s2, s2, s1
	s_addc_u32 s3, s3, 0
	global_load_dwordx4 v[52:55], v30, s[2:3] nt
	s_add_u32 s2, s2, s1
	s_addc_u32 s3, s3, 0
	global_load_dwordx4 v[56:59], v30, s[2:3] nt
	s_add_u32 s2, s2, s1
	s_addc_u32 s3, s3, 0
	global_load_dwordx4 v[60:63], v30, s[2:3] nt
; #define LAS __attribute__((address_space(3)))
; __device__ __forceinline__ unsigned pk2(float lo, float hi) { return pg8::cvt_pk_bf16(lo, hi); }
; __device__ __forceinline__ void wave_lds_fence() { asm volatile("s_waitcnt lgkmcnt(0)" ::: "memory"); }
; __device__ __forceinline__ void transpose_item(const float* W, int K, int N, bf16_t* WT, int mode, const float* gain, LAS float* scr, int item, int lane) {
;     ...
;         float v = (nn < N) ? __builtin_nontemporal_load(&W[(size_t)(k0 + kk) * N + nn]) : 0.f;
;         if (gain) v *= gain[k0 + kk];
;         scr[kk * 33 + (lane & 31)] = v * cs; }
;     wave_lds_fence();
;     const int c = lane & 7;
; #pragma unroll
;     for (int j = 0; j < 4; ++j) { const int n = (lane >> 3) + 8 * j; const LAS float* s = scr + (8 * c) * 33 + n;
;         u32x4 o; o.x = pk2(s[0 * 33], s[1 * 33]); o.y = pk2(s[2 * 33], s[3 * 33]); o.z = pk2(s[4 * 33], s[5 * 33]); o.w = pk2(s[6 * 33], s[7 * 33]);
;         const int ng = n0 + n; int dest = ng;
;         if (mode == 1) { const int hf = ng >= DSSM, jj = ng - DSSM * hf, jl = jj & 127; dest = (jj >> 7) * 256 + 128 * ((jl >> 2) & 1) + 32 * (jl >> 5) + 16 * hf + 4 * ((jl >> 3) & 3) + (jl & 3); }
;         else if (mode == 5 || (mode == 4 && ((ng >> 8) < 10 || (ng >> 8) > 13))) { const int c32 = ng & 31; dest = (ng & ~31) + 16 * ((c32 >> 2) & 1) + 4 * (c32 >> 3) + (c32 & 3); }
;         else if (mode == 2 || mode == 3) { const int jl = ng & 127; dest = (ng >> 7) * 256 + 128 * ((jl >> 2) & 1) + 32 * (jl >> 5) + 16 * (mode - 2) + 4 * ((jl >> 3) & 3) + (jl & 3); }
;         *(u32x4*)(WT + (size_t)dest * K + k0 + 8 * c) = o; }
;     wave_lds_fence();
.Lpro_loaded:
	s_cmp_eq_u32 s54, 0
	s_cbranch_scc1 .Lpro_nogain
	global_load_dword v64, v23, s[52:53]
	global_load_dword v65, v23, s[52:53] offset:32
	global_load_dword v66, v23, s[52:53] offset:64
	global_load_dword v67, v23, s[52:53] offset:96
	global_load_dword v68, v23, s[52:53] offset:128
	global_load_dword v69, v23, s[52:53] offset:160
	global_load_dword v70, v23, s[52:53] offset:192
	global_load_dword v71, v23, s[52:53] offset:224
	s_cmp_eq_u32 s11, 4
	s_cselect_b32 s0, 1, 0
	s_lshr_b32 s1, s22, 10
	s_cmp_eq_u32 s1, 1
	s_cselect_b32 s1, 1, 0
	s_and_b32 s0, s0, s1
	s_cmp_lg_u32 s0, 0
	s_cselect_b32 s55, 0x3e000000, 1.0
	s_waitcnt vmcnt(0)
	v_mul_f32_e32 v64, s55, v64
	v_mul_f32_e32 v65, s55, v65
	v_mul_f32_e32 v66, s55, v66
	v_mul_f32_e32 v67, s55, v67
	v_mul_f32_e32 v68, s55, v68
	v_mul_f32_e32 v69, s55, v69
	v_mul_f32_e32 v70, s55, v70
	v_mul_f32_e32 v71, s55, v71
	v_mul_f32_e32 v32, v32, v64
	v_mul_f32_e32 v33, v33, v64
	v_mul_f32_e32 v34, v34, v64
	v_mul_f32_e32 v35, v35, v64
	v_mul_f32_e32 v36, v36, v65
	v_mul_f32_e32 v37, v37, v65
	v_mul_f32_e32 v38, v38, v65
	v_mul_f32_e32 v39, v39, v65
	v_mul_f32_e32 v40, v40, v66
	v_mul_f32_e32 v41, v41, v66
	v_mul_f32_e32 v42, v42, v66
	v_mul_f32_e32 v43, v43, v66
	v_mul_f32_e32 v44, v44, v67
	v_mul_f32_e32 v45, v45, v67
	v_mul_f32_e32 v46, v46, v67
	v_mul_f32_e32 v47, v47, v67
	v_mul_f32_e32 v48, v48, v68
	v_mul_f32_e32 v49, v49, v68
	v_mul_f32_e32 v50, v50, v68
	v_mul_f32_e32 v51, v51, v68
	v_mul_f32_e32 v52, v52, v69
	v_mul_f32_e32 v53, v53, v69
	v_mul_f32_e32 v54, v54, v69
	v_mul_f32_e32 v55, v55, v69
	v_mul_f32_e32 v56, v56, v70
	v_mul_f32_e32 v57, v57, v70
	v_mul_f32_e32 v58, v58, v70
	v_mul_f32_e32 v59, v59, v70
	v_mul_f32_e32 v60, v60, v71
	v_mul_f32_e32 v61, v61, v71
	v_mul_f32_e32 v62, v62, v71
	v_mul_f32_e32 v63, v63, v71
.Lpro_nogain:
	s_waitcnt vmcnt(0)
	ds_write_b32 v24, v32
	ds_write_b32 v24, v33 offset:4
	ds_write_b32 v24, v34 offset:8
	ds_write_b32 v24, v35 offset:12
	ds_write_b32 v24, v36 offset:1056
	ds_write_b32 v24, v37 offset:1060
	ds_write_b32 v24, v38 offset:1064
	ds_write_b32 v24, v39 offset:1068
	ds_write_b32 v24, v40 offset:2112
	ds_write_b32 v24, v41 offset:2116
	ds_write_b32 v24, v42 offset:2120
	ds_write_b32 v24, v43 offset:2124
	ds_write_b32 v24, v44 offset:3168
	ds_write_b32 v24, v45 offset:3172
	ds_write_b32 v24, v46 offset:3176
	ds_write_b32 v24, v47 offset:3180
	ds_write_b32 v24, v48 offset:4224
	ds_write_b32 v24, v49 offset:4228
	ds_write_b32 v24, v50 offset:4232
	ds_write_b32 v24, v51 offset:4236
	ds_write_b32 v24, v52 offset:5280
	ds_write_b32 v24, v53 offset:5284
	ds_write_b32 v24, v54 offset:5288
	ds_write_b32 v24, v55 offset:5292
	ds_write_b32 v24, v56 offset:6336
	ds_write_b32 v24, v57 offset:6340
	ds_write_b32 v24, v58 offset:6344
	ds_write_b32 v24, v59 offset:6348
	ds_write_b32 v24, v60 offset:7392
	ds_write_b32 v24, v61 offset:7396
	ds_write_b32 v24, v62 offset:7400
	ds_write_b32 v24, v63 offset:7404
	s_cmp_eq_u32 s11, 0
	s_cbranch_scc1 .Lpro_m0
	s_cmp_ge_u32 s11, 4
	s_cbranch_scc1 .Lpro_m45
	s_cmp_eq_u32 s11, 1
	s_cselect_b32 s0, 0x3ff, -1
	s_and_b32 s0, s22, s0
	s_lshr_b32 s0, s0, 7
	s_lshl_b32 s0, s0, 8
	s_bfe_u32 s1, s22, 0x20005
	s_lshl_b32 s1, s1, 5
	s_or_b32 s0, s0, s1
	s_lshr_b32 s1, s22, 10
	s_sub_u32 s55, s11, 2
	s_cmp_eq_u32 s11, 1
	s_cselect_b32 s1, s1, s55
	s_lshl_b32 s1, s1, 4
	s_or_b32 s0, s0, s1
	v_add_u32_e32 v31, s0, v29
	s_mov_b32 s55, 4
	s_branch .Lpro_dest
.Lpro_m45:
	s_lshr_b32 s0, s22, 8
	s_sub_u32 s0, s0, 10
	s_cmp_lt_u32 s0, 4
	s_cselect_b32 s0, 1, 0
	s_cmp_eq_u32 s11, 4
	s_cselect_b32 s1, 1, 0
	s_and_b32 s0, s0, s1
	s_cmp_lg_u32 s0, 0
	s_cbranch_scc1 .Lpro_m0
	v_add_u32_e32 v31, s22, v28
	s_mov_b32 s55, 4
	s_branch .Lpro_dest
.Lpro_m0:
	v_add_u32_e32 v31, s22, v20
	s_mov_b32 s55, 8
.Lpro_dest:
	s_lshl_b32 s0, s23, 1
	s_waitcnt lgkmcnt(0)
	ds_read2_b32 v[72:73], v25 offset0:0 offset1:33
	ds_read2_b32 v[74:75], v25 offset0:66 offset1:99
	ds_read2_b32 v[76:77], v25 offset0:132 offset1:165
	ds_read2_b32 v[78:79], v25 offset0:198 offset1:231
	ds_read2_b32 v[80:81], v25 offset0:8 offset1:41
	ds_read2_b32 v[82:83], v25 offset0:74 offset1:107
	ds_read2_b32 v[84:85], v25 offset0:140 offset1:173
	ds_read2_b32 v[86:87], v25 offset0:206 offset1:239
	s_mul_i32 s1, s55, 0
	v_add_u32_e32 v120, s1, v31
	v_mul_lo_u32 v120, v120, s20
	v_add3_u32 v120, v120, v22, s0
	s_mul_i32 s1, s55, 1
	v_add_u32_e32 v121, s1, v31
	v_mul_lo_u32 v121, v121, s20
	v_add3_u32 v121, v121, v22, s0
	s_mul_i32 s1, s55, 2
	v_add_u32_e32 v122, s1, v31
	v_mul_lo_u32 v122, v122, s20
	v_add3_u32 v122, v122, v22, s0
	s_mul_i32 s1, s55, 3
	v_add_u32_e32 v123, s1, v31
	v_mul_lo_u32 v123, v123, s20
	v_add3_u32 v123, v123, v22, s0
	s_waitcnt lgkmcnt(4)
	ds_read2_b32 v[88:89], v25 offset0:16 offset1:49
	ds_read2_b32 v[90:91], v25 offset0:82 offset1:115
	ds_read2_b32 v[92:93], v25 offset0:148 offset1:181
	ds_read2_b32 v[94:95], v25 offset0:214 offset1:247
	v_cvt_pk_bf16_f32 v104, v72, v73
	v_cvt_pk_bf16_f32 v105, v74, v75
	v_cvt_pk_bf16_f32 v106, v76, v77
	v_cvt_pk_bf16_f32 v107, v78, v79
	global_store_dwordx4 v120, v[104:107], s[4:5]
	s_waitcnt lgkmcnt(4)
	ds_read2_b32 v[96:97], v25 offset0:24 offset1:57
	ds_read2_b32 v[98:99], v25 offset0:90 offset1:123
	ds_read2_b32 v[100:101], v25 offset0:156 offset1:189
	ds_read2_b32 v[102:103], v25 offset0:222 offset1:255
	v_cvt_pk_bf16_f32 v108, v80, v81
	v_cvt_pk_bf16_f32 v109, v82, v83
	v_cvt_pk_bf16_f32 v110, v84, v85
	v_cvt_pk_bf16_f32 v111, v86, v87
	global_store_dwordx4 v121, v[108:111], s[4:5]
	s_waitcnt lgkmcnt(4)
	v_cvt_pk_bf16_f32 v112, v88, v89
	v_cvt_pk_bf16_f32 v113, v90, v91
	v_cvt_pk_bf16_f32 v114, v92, v93
	v_cvt_pk_bf16_f32 v115, v94, v95
	global_store_dwordx4 v122, v[112:115], s[4:5]
	s_waitcnt lgkmcnt(0)
	v_cvt_pk_bf16_f32 v116, v96, v97
	v_cvt_pk_bf16_f32 v117, v98, v99
	v_cvt_pk_bf16_f32 v118, v100, v101
	v_cvt_pk_bf16_f32 v119, v102, v103
	global_store_dwordx4 v123, v[116:119], s[4:5]
	s_add_u32 s16, s16, s12
	s_cmp_lt_u32 s16, 95520
	s_waitcnt lgkmcnt(0)
	s_cbranch_scc1 .Lpro_loop

; #define LAS __attribute__((address_space(3)))
; __device__ __forceinline__ void nsa_wave(CArgs* Ap, int l, int b, int g, int tq0, const LAS float* lut, LAS float* imp, int lane) {
;     ...
;     else {
;         const int sq = lane >> 4, tsel = tq0 + sq; (void)tsel;
;         float sc[8];
; #pragma unroll
;         for (int jj = 0; jj < 8; ++jj) { const int j = n16 + 16 * jj;
;             float v;
;             if (j > cur) v = -1.f;
;             else if (j == 0 || j == cur || j == cur - 1) v = 1e4f;
;             else { const LAS float* ip = imp + sq * 512 + 4 * j; v = ip[0] + 2.f * (ip[-1] + ip[-2] + ip[-3]) + ip[-4]; }
;             sc[jj] = v; }
.Ltk_full:
	s_add_i32 s22, s21, -1
	v_lshrrev_b32_e32 v106, 4, v89
	v_lshl_add_u32 v106, v106, 11, s93
	v_lshl_add_u32 v106, v128, 4, v106
	v_add_u32_e32 v107, -16, v106
	v_or_b32_e32 v99, 16, v128
	v_or_b32_e32 v100, 32, v128
	v_or_b32_e32 v101, 48, v128
	v_or_b32_e32 v102, 64, v128
	v_or_b32_e32 v103, 80, v128
	v_or_b32_e32 v104, 96, v128
	v_or_b32_e32 v105, 112, v128
	ds_read_b128 v[24:27], v107
	ds_read_b32 v56, v106
	ds_read_b128 v[28:31], v107 offset:256
	ds_read_b32 v57, v106 offset:256
	ds_read_b128 v[32:35], v107 offset:512
	ds_read_b32 v58, v106 offset:512
	ds_read_b128 v[36:39], v107 offset:768
	ds_read_b32 v59, v106 offset:768
	ds_read_b128 v[40:43], v107 offset:1024
	ds_read_b32 v60, v106 offset:1024
	ds_read_b128 v[44:47], v107 offset:1280
	ds_read_b32 v61, v106 offset:1280
	ds_read_b128 v[48:51], v107 offset:1536
	ds_read_b32 v62, v106 offset:1536
	ds_read_b128 v[52:55], v107 offset:1792
	ds_read_b32 v63, v106 offset:1792
	v_mov_b32_e32 v64, 0x461c4000
	v_cmp_eq_u32_e64 s[46:47], s21, v128
	v_cmp_eq_u32_e64 s[48:49], s22, v128
	s_or_b64 s[50:51], s[46:47], s[48:49]
	s_or_b64 s[50:51], s[50:51], s[4:5]
	v_cmp_eq_u32_e64 s[46:47], s21, v99
	v_cmp_eq_u32_e64 s[48:49], s22, v99
	s_or_b64 s[52:53], s[46:47], s[48:49]
	v_cmp_eq_u32_e64 s[46:47], s21, v100
	v_cmp_eq_u32_e64 s[48:49], s22, v100
	s_or_b64 s[54:55], s[46:47], s[48:49]
	v_cmp_eq_u32_e64 s[46:47], s21, v101
	v_cmp_eq_u32_e64 s[48:49], s22, v101
	s_or_b64 s[56:57], s[46:47], s[48:49]
	v_cmp_eq_u32_e64 s[46:47], s21, v102
	v_cmp_eq_u32_e64 s[48:49], s22, v102
	s_or_b64 s[58:59], s[46:47], s[48:49]
	v_cmp_eq_u32_e64 s[46:47], s21, v103
	v_cmp_eq_u32_e64 s[48:49], s22, v103
	s_or_b64 s[60:61], s[46:47], s[48:49]
	v_cmp_eq_u32_e64 s[46:47], s21, v104
	v_cmp_eq_u32_e64 s[48:49], s22, v104
	s_or_b64 s[62:63], s[46:47], s[48:49]
	v_cmp_eq_u32_e64 s[46:47], s21, v105
	v_cmp_eq_u32_e64 s[48:49], s22, v105
	s_or_b64 s[64:65], s[46:47], s[48:49]
	s_waitcnt lgkmcnt(14)
	v_add_f32_e32 v26, v27, v26
	v_add_f32_e32 v25, v26, v25
	v_fmac_f32_e32 v56, 2.0, v25
	v_add_f32_e32 v228, v24, v56
	s_waitcnt lgkmcnt(12)
	v_add_f32_e32 v30, v31, v30
	v_add_f32_e32 v29, v30, v29
	v_fmac_f32_e32 v57, 2.0, v29
	v_add_f32_e32 v229, v28, v57
	s_waitcnt lgkmcnt(10)
	v_add_f32_e32 v34, v35, v34
	v_add_f32_e32 v33, v34, v33
	v_fmac_f32_e32 v58, 2.0, v33
	v_add_f32_e32 v230, v32, v58
	s_waitcnt lgkmcnt(8)
	v_add_f32_e32 v38, v39, v38
	v_add_f32_e32 v37, v38, v37
	v_fmac_f32_e32 v59, 2.0, v37
	v_add_f32_e32 v231, v36, v59
	s_waitcnt lgkmcnt(6)
	v_add_f32_e32 v42, v43, v42
	v_add_f32_e32 v41, v42, v41
	v_fmac_f32_e32 v60, 2.0, v41
	v_add_f32_e32 v232, v40, v60
	s_waitcnt lgkmcnt(4)
	v_add_f32_e32 v46, v47, v46
	v_add_f32_e32 v45, v46, v45
	v_fmac_f32_e32 v61, 2.0, v45
	v_add_f32_e32 v233, v44, v61
	s_waitcnt lgkmcnt(2)
	v_add_f32_e32 v50, v51, v50
	v_add_f32_e32 v49, v50, v49
	v_fmac_f32_e32 v62, 2.0, v49
	v_add_f32_e32 v234, v48, v62
	s_waitcnt lgkmcnt(0)
	v_add_f32_e32 v54, v55, v54
	v_add_f32_e32 v53, v54, v53
	v_fmac_f32_e32 v63, 2.0, v53
	v_add_f32_e32 v235, v52, v63
	v_cndmask_b32_e64 v228, v228, v64, s[50:51]
	v_cndmask_b32_e64 v229, v229, v64, s[52:53]
	v_cndmask_b32_e64 v230, v230, v64, s[54:55]
	v_cndmask_b32_e64 v231, v231, v64, s[56:57]
	v_cndmask_b32_e64 v232, v232, v64, s[58:59]
	v_cndmask_b32_e64 v233, v233, v64, s[60:61]
	v_cndmask_b32_e64 v234, v234, v64, s[62:63]
	v_cndmask_b32_e64 v235, v235, v64, s[64:65]
	v_cmp_ge_i32_e64 s[52:53], s21, v99
	v_cmp_ge_i32_e64 s[54:55], s21, v100
	v_cmp_ge_i32_e64 s[56:57], s21, v101
	v_cmp_ge_i32_e64 s[58:59], s21, v102
	v_cmp_ge_i32_e64 s[60:61], s21, v103
	v_cmp_ge_i32_e64 s[62:63], s21, v104
	v_cmp_ge_i32_e64 s[64:65], s21, v105
	v_cndmask_b32_e64 v229, -1.0, v229, s[52:53]
	v_cndmask_b32_e64 v230, -1.0, v230, s[54:55]
	v_cndmask_b32_e64 v231, -1.0, v231, s[56:57]
	v_cndmask_b32_e64 v232, -1.0, v232, s[58:59]
	v_cndmask_b32_e64 v233, -1.0, v233, s[60:61]
	v_cndmask_b32_e64 v234, -1.0, v234, s[62:63]
	v_cndmask_b32_e64 v235, -1.0, v235, s[64:65]
	s_mov_b32 s23, 0
; __device__ __forceinline__ void nsa_wave(CArgs* Ap, int l, int b, int g, int tq0, const LAS float* lut, LAS float* imp, int lane) {
;     ...
;         for (int s = 0; s < 16; ++s) {
;             float bv = sc[0]; int bj = n16;
; #pragma unroll
;             for (int jj = 1; jj < 8; ++jj) if (sc[jj] > bv) { bv = sc[jj]; bj = n16 + 16 * jj; }
; #pragma unroll
;             for (int off = 1; off < 16; off <<= 1) { const float ov = __shfl_xor(bv, off); const int oj = __shfl_xor(bj, off); if (ov > bv || (ov == bv && oj < bj)) { bv = ov; bj = oj; } }
;             if (n16 == s) selreg = (bv >= 0.f) ? bj : -1;
; #pragma unroll
;             for (int jj = 0; jj < 8; ++jj) if (bj == n16 + 16 * jj) sc[jj] = -2.f;
;         }
;     }
;     if (cur >= 16) {
;         const int fj = selreg;
;         const int key = (fj < 0) ? ((1 << 20) + n16) : ((fj == 0 || fj == cur || fj == cur - 1) ? fj : (1 << 10) + fj);
;         int rank = 0;
; #pragma unroll
;         for (int o = 1; o < 16; ++o) { const int other = __shfl(key, (lane & 48) | ((n16 + o) & 15)); rank += (other < key) ? 1 : 0; }
;         selreg = __builtin_amdgcn_ds_permute(((lane & 48) | rank) << 2, fj);
.Ltk_loop:
	v_max3_f32 v238, v228, v229, v230
	v_max3_f32 v239, v231, v232, v233
	v_max3_f32 v238, v234, v235, v238
	v_max_f32_e32 v236, v238, v239
	s_nop 1
	v_max_f32_dpp v236, v236, v236 quad_perm:[1,0,3,2] row_mask:0xf bank_mask:0xf
	s_nop 1
	v_max_f32_dpp v236, v236, v236 quad_perm:[2,3,0,1] row_mask:0xf bank_mask:0xf
	s_nop 1
	v_max_f32_dpp v236, v236, v236 row_half_mirror row_mask:0xf bank_mask:0xf
	s_nop 1
	v_max_f32_dpp v236, v236, v236 row_mirror row_mask:0xf bank_mask:0xf
	v_cmp_eq_f32_e64 s[50:51], v228, v236
	v_cmp_eq_f32_e64 s[52:53], v229, v236
	v_cmp_eq_f32_e64 s[54:55], v230, v236
	v_cmp_eq_f32_e64 s[56:57], v231, v236
	v_cmp_eq_f32_e64 s[58:59], v232, v236
	v_cmp_eq_f32_e64 s[60:61], v233, v236
	v_cmp_eq_f32_e64 s[62:63], v234, v236
	v_cmp_eq_f32_e64 s[64:65], v235, v236
	v_bfrev_b32_e32 v239, -2
	v_cndmask_b32_e64 v244, v239, v128, s[50:51]
	v_cndmask_b32_e64 v245, v239, v99, s[52:53]
	v_cndmask_b32_e64 v246, v239, v100, s[54:55]
	v_cndmask_b32_e64 v247, v239, v101, s[56:57]
	v_cndmask_b32_e64 v248, v239, v102, s[58:59]
	v_cndmask_b32_e64 v249, v239, v103, s[60:61]
	v_cndmask_b32_e64 v250, v239, v104, s[62:63]
	v_cndmask_b32_e64 v251, v239, v105, s[64:65]
	v_min3_u32 v238, v244, v245, v246
	v_min3_u32 v239, v247, v248, v249
	v_min3_u32 v238, v250, v251, v238
	v_min_u32_e32 v237, v238, v239
	s_nop 1
	v_min_u32_dpp v237, v237, v237 quad_perm:[1,0,3,2] row_mask:0xf bank_mask:0xf
	s_nop 1
	v_min_u32_dpp v237, v237, v237 quad_perm:[2,3,0,1] row_mask:0xf bank_mask:0xf
	s_nop 1
	v_min_u32_dpp v237, v237, v237 row_half_mirror row_mask:0xf bank_mask:0xf
	s_nop 1
	v_min_u32_dpp v237, v237, v237 row_mirror row_mask:0xf bank_mask:0xf
	v_cmp_le_f32_e64 s[46:47], 0, v236
	v_cmp_eq_u32_e64 s[48:49], s23, v128
	v_cmp_eq_u32_e64 s[50:51], v128, v237
	v_cmp_eq_u32_e64 s[52:53], v99, v237
	v_cmp_eq_u32_e64 s[54:55], v100, v237
	v_cmp_eq_u32_e64 s[56:57], v101, v237
	v_cmp_eq_u32_e64 s[58:59], v102, v237
	v_cmp_eq_u32_e64 s[60:61], v103, v237
	v_cmp_eq_u32_e64 s[62:63], v104, v237
	v_cmp_eq_u32_e64 s[64:65], v105, v237
	v_cndmask_b32_e64 v238, -1, v237, s[46:47]
	v_mov_b32_e32 v239, -2.0
	s_add_i32 s23, s23, 1
	v_cndmask_b32_e64 v210, v210, v238, s[48:49]
	v_cndmask_b32_e64 v228, v228, v239, s[50:51]
	v_cndmask_b32_e64 v229, v229, v239, s[52:53]
	v_cndmask_b32_e64 v230, v230, v239, s[54:55]
	v_cndmask_b32_e64 v231, v231, v239, s[56:57]
	v_cndmask_b32_e64 v232, v232, v239, s[58:59]
	v_cndmask_b32_e64 v233, v233, v239, s[60:61]
	v_cndmask_b32_e64 v234, v234, v239, s[62:63]
	v_cndmask_b32_e64 v235, v235, v239, s[64:65]
	s_cmp_lt_u32 s23, 16
	s_cbranch_scc1 .Ltk_loop
	v_cmp_eq_u32_e64 s[46:47], 0, v210
	v_cmp_eq_u32_e64 s[48:49], s21, v210
	v_cmp_eq_u32_e64 s[50:51], s22, v210
	v_cmp_lt_i32_e64 s[52:53], -1, v210
	v_add_u32_e32 v240, 0x400, v210
	s_or_b64 s[46:47], s[46:47], s[48:49]
	s_or_b64 s[46:47], s[46:47], s[50:51]
	v_cndmask_b32_e64 v240, v240, v210, s[46:47]
	v_cndmask_b32_e64 v240, v164, v240, s[52:53]
	s_nop 1
	v_sub_u32_dpp v25, v240, v240 row_ror:1 row_mask:0xf bank_mask:0xf
	v_sub_u32_dpp v26, v240, v240 row_ror:2 row_mask:0xf bank_mask:0xf
	v_sub_u32_dpp v27, v240, v240 row_ror:3 row_mask:0xf bank_mask:0xf
	v_sub_u32_dpp v28, v240, v240 row_ror:4 row_mask:0xf bank_mask:0xf
	v_sub_u32_dpp v29, v240, v240 row_ror:5 row_mask:0xf bank_mask:0xf
	v_sub_u32_dpp v30, v240, v240 row_ror:6 row_mask:0xf bank_mask:0xf
	v_sub_u32_dpp v31, v240, v240 row_ror:7 row_mask:0xf bank_mask:0xf
	v_sub_u32_dpp v32, v240, v240 row_ror:8 row_mask:0xf bank_mask:0xf
	v_sub_u32_dpp v33, v240, v240 row_ror:9 row_mask:0xf bank_mask:0xf
	v_sub_u32_dpp v34, v240, v240 row_ror:10 row_mask:0xf bank_mask:0xf
	v_sub_u32_dpp v35, v240, v240 row_ror:11 row_mask:0xf bank_mask:0xf
	v_sub_u32_dpp v36, v240, v240 row_ror:12 row_mask:0xf bank_mask:0xf
	v_sub_u32_dpp v37, v240, v240 row_ror:13 row_mask:0xf bank_mask:0xf
	v_sub_u32_dpp v38, v240, v240 row_ror:14 row_mask:0xf bank_mask:0xf
	v_sub_u32_dpp v39, v240, v240 row_ror:15 row_mask:0xf bank_mask:0xf
	v_lshrrev_b32_e32 v25, 31, v25
	v_lshrrev_b32_e32 v26, 31, v26
	v_lshrrev_b32_e32 v27, 31, v27
	v_lshrrev_b32_e32 v28, 31, v28
	v_lshrrev_b32_e32 v29, 31, v29
	v_lshrrev_b32_e32 v30, 31, v30
	v_lshrrev_b32_e32 v31, 31, v31
	v_lshrrev_b32_e32 v32, 31, v32
	v_lshrrev_b32_e32 v33, 31, v33
	v_lshrrev_b32_e32 v34, 31, v34
	v_lshrrev_b32_e32 v35, 31, v35
	v_lshrrev_b32_e32 v36, 31, v36
	v_lshrrev_b32_e32 v37, 31, v37
	v_lshrrev_b32_e32 v38, 31, v38
	v_lshrrev_b32_e32 v39, 31, v39
	v_add3_u32 v241, v25, v26, v27
	v_add3_u32 v241, v241, v28, v29
	v_add3_u32 v241, v241, v30, v31
	v_add3_u32 v241, v241, v32, v33
	v_add3_u32 v241, v241, v34, v35
	v_add3_u32 v241, v241, v36, v37
	v_add3_u32 v241, v241, v38, v39
	v_or_b32_e32 v241, v241, v129
	v_lshlrev_b32_e32 v241, 2, v241
	ds_permute_b32 v210, v241, v210

; __device__ __forceinline__ void nsa_wave(CArgs* Ap, int l, int b, int g, int tq0, const LAS float* lut, LAS float* imp, int lane) {
;     ...
;         const int nh = 2 * nvalid, h0 = 2 * ns;
;         long kq[4][2][2], vq[4][4];
;         if (h0 < nh) {
; #pragma unroll
;             for (int q2 = 0; q2 < 4; ++q2) { int j = __builtin_amdgcn_readlane(selreg, 16 * q2 + ns); j = j < 0 ? 0 : j; load_kh8(kq[q2], Ks8 + (size_t)j * 4096, 0, lane); load_vh8(vq[q2], Vs8 + (size_t)j * 4096, 0, lane); } }
;         for (int hs = h0; hs < nh; ++hs) {
;             const int s = hs >> 1, hh = hs & 1;
;             const int jm = __shfl(selreg, 16 * qi + s);
;             f32x4 acc[2];
;             acc[0] = (f32x4){0.f, 0.f, 0.f, 0.f}; acc[1] = (f32x4){0.f, 0.f, 0.f, 0.f};
; #pragma unroll
;             for (int q2 = 0; q2 < 4; ++q2) { long qm[2]; qm[0] = (qi == q2) ? q8[0] : 0l; qm[1] = (qi == q2) ? q8[1] : 0l; qk_acch8(acc, kq[q2], qm); }
;             const bool more = hs + 1 < nh; const int s1 = (hs + 1) >> 1, h1 = (hs + 1) & 1;
;             int jn[4];
; #pragma unroll
;             for (int q2 = 0; q2 < 4; ++q2) { int j = more ? __builtin_amdgcn_readlane(selreg, 16 * q2 + s1) : 0; jn[q2] = j < 0 ? 0 : j; }
;             if (more) {
; #pragma unroll
;                 for (int q2 = 0; q2 < 4; ++q2) load_kh8(kq[q2], Ks8 + (size_t)jn[q2] * 4096, h1, lane); }
.LBB0_1259:
	s_lshl_b32 s22, s22, 1
	s_cmp_gt_i32 s23, s22
	s_cbranch_scc1 .LBB0_1279
	s_mov_b32 s32, s24
	s_lshr_b32 s42, s22, 1
	s_add_i32 s42, s42, 1
	v_or_b32_e32 v229, 0x800, v84
	v_readlane_b32 s25, v210, s32
	s_max_i32 s72, s25, 0
	s_lshl_b64 s[36:37], s[72:73], 12
	s_add_i32 s25, s32, 16
	v_readlane_b32 s25, v210, s25
	s_max_i32 s72, s25, 0
	s_lshl_b64 s[38:39], s[72:73], 12
	s_xor_b32 s25, s32, 32
	v_readlane_b32 s25, v210, s25
	s_max_i32 s72, s25, 0
	s_lshl_b64 s[40:41], s[72:73], 12
	s_add_i32 s25, s32, 48
	v_readlane_b32 s25, v210, s25
	s_max_i32 s72, s25, 0
	s_lshl_b64 s[84:85], s[72:73], 12
	ds_write_b128 v93, v[0:3] offset:4096
	ds_write_b128 v93, v[4:7] offset:5120
	ds_read_b32 v228, v206 offset:16368
	s_add_u32 s48, s96, s36
	s_addc_u32 s49, s97, s37
	global_load_dwordx4 v[32:35], v84, s[48:49]
	global_load_dwordx4 v[36:39], v84, s[48:49] offset:1024
	s_add_u32 s48, s96, s38
	s_addc_u32 s49, s97, s39
	global_load_dwordx4 v[48:51], v84, s[48:49]
	global_load_dwordx4 v[52:55], v84, s[48:49] offset:1024
	s_add_u32 s48, s96, s40
	s_addc_u32 s49, s97, s41
	global_load_dwordx4 v[64:67], v84, s[48:49]
	global_load_dwordx4 v[68:71], v84, s[48:49] offset:1024
	s_add_u32 s48, s96, s84
	s_addc_u32 s49, s97, s85
	global_load_dwordx4 v[112:115], v84, s[48:49]
	global_load_dwordx4 v[116:119], v84, s[48:49] offset:1024
	s_add_u32 s48, s0, s36
	s_addc_u32 s49, s1, s37
	global_load_dwordx4 v[40:43], v84, s[48:49]
	global_load_dwordx4 v[44:47], v84, s[48:49] offset:1024
	s_add_u32 s48, s0, s38
	s_addc_u32 s49, s1, s39
	global_load_dwordx4 v[56:59], v84, s[48:49]
	global_load_dwordx4 v[60:63], v84, s[48:49] offset:1024
	s_add_u32 s48, s0, s40
	s_addc_u32 s49, s1, s41
	global_load_dwordx4 v[74:77], v84, s[48:49]
	global_load_dwordx4 v[78:81], v84, s[48:49] offset:1024
	s_add_u32 s48, s0, s84
	s_addc_u32 s49, s1, s85
	global_load_dwordx4 v[106:109], v84, s[48:49]
	global_load_dwordx4 v[122:125], v84, s[48:49] offset:1024
	s_add_u32 s48, s96, s36
	s_addc_u32 s49, s97, s37
	global_load_dwordx4 v[184:187], v229, s[48:49]
	global_load_dwordx4 v[188:191], v229, s[48:49] offset:1024
	s_add_u32 s48, s96, s38
	s_addc_u32 s49, s97, s39
	global_load_dwordx4 v[192:195], v229, s[48:49]
	global_load_dwordx4 v[196:199], v229, s[48:49] offset:1024
	s_add_u32 s48, s96, s40
	s_addc_u32 s49, s97, s41
	global_load_dwordx4 v[230:233], v229, s[48:49]
	global_load_dwordx4 v[234:237], v229, s[48:49] offset:1024
	s_add_u32 s48, s96, s84
	s_addc_u32 s49, s97, s85
	global_load_dwordx4 v[238:241], v229, s[48:49]
	global_load_dwordx4 v[242:245], v229, s[48:49] offset:1024
	s_add_u32 s48, s0, s36
	s_addc_u32 s49, s1, s37
	global_load_dwordx4 v[134:137], v229, s[48:49]
	global_load_dwordx4 v[138:141], v229, s[48:49] offset:1024
	s_add_u32 s48, s0, s38
	s_addc_u32 s49, s1, s39
	global_load_dwordx4 v[152:155], v229, s[48:49]
	global_load_dwordx4 v[156:159], v229, s[48:49] offset:1024
	s_add_u32 s48, s0, s40
	s_addc_u32 s49, s1, s41
	global_load_dwordx4 v[160:163], v229, s[48:49]
	global_load_dwordx4 v[246:249], v229, s[48:49] offset:1024
	s_add_u32 s48, s0, s84
	s_addc_u32 s49, s1, s85
	global_load_dwordx4 v[0:3], v229, s[48:49]
	global_load_dwordx4 v[4:7], v229, s[48:49] offset:1024
	v_cndmask_b32_e64 v83, 0, v103, s[6:7]
	v_cndmask_b32_e64 v82, 0, v102, s[6:7]
	v_cndmask_b32_e64 v99, 0, v103, s[8:9]
	v_cndmask_b32_e64 v98, 0, v102, s[8:9]
	v_cndmask_b32_e64 v101, 0, v103, s[10:11]
	v_cndmask_b32_e64 v100, 0, v102, s[10:11]
	v_cndmask_b32_e64 v103, 0, v103, s[12:13]
	v_cndmask_b32_e64 v102, 0, v102, s[12:13]
	v_cndmask_b32_e64 v105, 0, v127, s[6:7]
	v_cndmask_b32_e64 v104, 0, v126, s[6:7]
	v_cndmask_b32_e64 v111, 0, v127, s[8:9]
	v_cndmask_b32_e64 v110, 0, v126, s[8:9]
	v_cndmask_b32_e64 v121, 0, v127, s[10:11]
	v_cndmask_b32_e64 v120, 0, v126, s[10:11]
	v_cndmask_b32_e64 v127, 0, v127, s[12:13]
	v_cndmask_b32_e64 v126, 0, v126, s[12:13]
	s_lshl_b32 s24, s24, 6
	s_add_i32 s25, s32, 1
	s_cmp_lt_i32 s25, s42
	s_cbranch_scc0 .Lsl_last
.Lsl_steady:
	s_add_i32 s23, s32, 1
	v_readlane_b32 s25, v210, s23
	s_max_i32 s72, s25, 0
	s_lshl_b64 s[26:27], s[72:73], 12
	s_add_i32 s25, s23, 16
	v_readlane_b32 s25, v210, s25
	s_max_i32 s72, s25, 0
	s_lshl_b64 s[28:29], s[72:73], 12
	s_xor_b32 s25, s23, 32
	v_readlane_b32 s25, v210, s25
	s_max_i32 s72, s25, 0
	s_lshl_b64 s[30:31], s[72:73], 12
	s_add_i32 s25, s23, 48
	v_readlane_b32 s25, v210, s25
	s_max_i32 s72, s25, 0
	s_lshl_b64 s[34:35], s[72:73], 12
	s_waitcnt vmcnt(31)
	v_mfma_f32_16x16x32_fp8_fp8 v[24:27], v[32:33], v[82:83], 0
	v_add_u32_e32 v150, s32, v201
	v_and_or_b32 v150, v150, 63, v73
	s_waitcnt vmcnt(30)
	v_mfma_f32_16x16x32_fp8_fp8 v[28:31], v[36:37], v[82:83], 0
	v_lshlrev_b32_e32 v150, 2, v150
	ds_bpermute_b32 v214, v150, v210
	v_mfma_f32_16x16x32_fp8_fp8 v[24:27], v[34:35], v[104:105], v[24:27]
	v_mfma_f32_16x16x32_fp8_fp8 v[28:31], v[38:39], v[104:105], v[28:31]
	s_waitcnt vmcnt(29)
	v_mfma_f32_16x16x32_fp8_fp8 v[24:27], v[48:49], v[98:99], v[24:27]
	s_waitcnt vmcnt(28)
	v_mfma_f32_16x16x32_fp8_fp8 v[28:31], v[52:53], v[98:99], v[28:31]
	v_mfma_f32_16x16x32_fp8_fp8 v[24:27], v[50:51], v[110:111], v[24:27]
	v_mfma_f32_16x16x32_fp8_fp8 v[28:31], v[54:55], v[110:111], v[28:31]
	s_waitcnt vmcnt(27)
	v_mfma_f32_16x16x32_fp8_fp8 v[24:27], v[64:65], v[100:101], v[24:27]
	s_waitcnt vmcnt(26)
	v_mfma_f32_16x16x32_fp8_fp8 v[28:31], v[68:69], v[100:101], v[28:31]
	v_mfma_f32_16x16x32_fp8_fp8 v[24:27], v[66:67], v[120:121], v[24:27]
	v_mfma_f32_16x16x32_fp8_fp8 v[28:31], v[70:71], v[120:121], v[28:31]
	s_waitcnt vmcnt(25)
	v_mfma_f32_16x16x32_fp8_fp8 v[24:27], v[112:113], v[102:103], v[24:27]
	s_waitcnt vmcnt(24)
	v_mfma_f32_16x16x32_fp8_fp8 v[28:31], v[116:117], v[102:103], v[28:31]
	v_mfma_f32_16x16x32_fp8_fp8 v[24:27], v[114:115], v[126:127], v[24:27]
	v_mfma_f32_16x16x32_fp8_fp8 v[28:31], v[118:119], v[126:127], v[28:31]
	s_add_u32 s48, s96, s26
	s_addc_u32 s49, s97, s27
	global_load_dwordx4 v[32:35], v84, s[48:49]
	global_load_dwordx4 v[36:39], v84, s[48:49] offset:1024
	s_add_u32 s48, s96, s28
	s_addc_u32 s49, s97, s29
	global_load_dwordx4 v[48:51], v84, s[48:49]
	global_load_dwordx4 v[52:55], v84, s[48:49] offset:1024
	s_add_u32 s48, s96, s30
	s_addc_u32 s49, s97, s31
	global_load_dwordx4 v[64:67], v84, s[48:49]
	global_load_dwordx4 v[68:71], v84, s[48:49] offset:1024
	s_add_u32 s48, s96, s34
	s_addc_u32 s49, s97, s35
	global_load_dwordx4 v[112:115], v84, s[48:49]
	global_load_dwordx4 v[116:119], v84, s[48:49] offset:1024
; #define LAS __attribute__((address_space(3)))
; __device__ __forceinline__ float fexp(float x) { return __expf(x); }
; template <int MODE>
; __device__ __forceinline__ void softmax_half(f32x4 (&acc)[2], int base, bool ok, int t, int g4, const LAS float* lutg, SmState& st, f32x4 (&O)[4], bf16x8& pB) {
;     float mx = -1e30f; unsigned vm = 0u;
; #pragma unroll
;     for (int nt = 0; nt < 2; ++nt)
; #pragma unroll
;         for (int i = 0; i < 4; ++i) {
;             const int key = base + 16 * nt + 4 * g4 + i;
;             const int dist = t - key;
;             bool valid = dist >= 0;
;             if (MODE == 1) valid = valid && ok;
;             if (MODE == 2) valid = valid && dist < 512;
;             int dc = dist < 0 ? 0 : dist; dc = dc > 1023 ? 1023 : dc;
;             const float lg = acc[nt][i] + lutg[dc * 4];
;             acc[nt][i] = lg;
;             if (valid) { mx = fmaxf(mx, lg); vm |= 1u << (nt * 4 + i); }
;         }
;     mx = fmaxf(mx, __shfl_xor(mx, 16)); mx = fmaxf(mx, __shfl_xor(mx, 32));
;     const float mn = fmaxf(st.m, mx);
;     const float sc = fexp(st.m - mn);
;     float ls = 0.f;
; #pragma unroll
;     for (int nt = 0; nt < 2; ++nt)
; #pragma unroll
;         for (int i = 0; i < 4; ++i) { const float p = ((vm >> (nt * 4 + i)) & 1u) ? fexp(acc[nt][i] - mn) : 0.f; acc[nt][i] = p; ls += p; }
;     st.l = st.l * sc + ls; st.m = mn;
.Lsla_1271:
	s_and_b32 s50, s24, 32
	s_waitcnt lgkmcnt(0)
	v_mov_b32_e32 v165, v214
	v_lshl_or_b32 v150, v214, 6, s50
	v_sub_u32_e32 v150, v211, v150
	v_cmp_lt_i32_e32 vcc, -1, v214
	v_cmp_lt_i32_e64 s[48:49], s75, v150
	s_and_b64 s[48:49], vcc, s[48:49]
	s_nop 0
	v_cndmask_b32_e64 v150, 0, 1, s[48:49]
	v_cmp_ne_u32_e32 vcc, 0, v150
	s_cmp_lg_u64 vcc, exec
	s_mov_b64 s[48:49], -1
	s_cbranch_scc0 .Lsla_1273
	v_max_i32_e32 v150, 0, v214
	v_lshlrev_b32_e32 v150, 6, v150
	v_or3_b32 v150, v150, s50, v88
	v_sub_u32_e32 v151, v72, v150
	v_or_b32_e32 v213, v151, v214
	v_med3_i32 v151, v151, 0, v181
	v_lshl_add_u32 v151, v151, 4, v206
	v_xad_u32 v215, v150, -1, v72
	ds_read_b32 v151, v151
	v_or_b32_e32 v216, v215, v214
	v_med3_i32 v215, v215, 0, v181
	v_lshl_add_u32 v215, v215, 4, v206
	ds_read_b32 v215, v215
	s_waitcnt lgkmcnt(1)
	v_add_f32_e32 v151, v24, v151
	v_cmp_lt_i32_e32 vcc, -1, v213
	v_max_f32_e32 v213, 0xf149f2ca, v151
	v_cmp_lt_i32_e64 s[48:49], -1, v216
	v_cndmask_b32_e32 v213, v182, v213, vcc
	s_waitcnt lgkmcnt(0)
	v_add_f32_e32 v215, v25, v215
	v_max_f32_e32 v216, v213, v215
	v_cndmask_b32_e64 v213, v213, v216, s[48:49]
	v_or_b32_e32 v216, 2, v150
	v_sub_u32_e32 v216, v72, v216
	v_or_b32_e32 v217, v216, v214
	v_med3_i32 v216, v216, 0, v181
	v_lshl_add_u32 v216, v216, 4, v206
	ds_read_b32 v216, v216
	v_cmp_lt_i32_e64 s[50:51], -1, v217
	s_waitcnt lgkmcnt(0)
	v_add_f32_e32 v218, v26, v216
	v_max_f32_e32 v216, v213, v218
	v_cndmask_b32_e64 v213, v213, v216, s[50:51]
	v_or_b32_e32 v216, 3, v150
	v_sub_u32_e32 v216, v72, v216
	v_or_b32_e32 v217, v216, v214
	v_med3_i32 v216, v216, 0, v181
	v_lshl_add_u32 v216, v216, 4, v206
	ds_read_b32 v216, v216
	v_cmp_lt_i32_e64 s[52:53], -1, v217
	s_waitcnt lgkmcnt(0)
	v_add_f32_e32 v219, v27, v216
	v_max_f32_e32 v216, v213, v219
	v_cndmask_b32_e64 v213, v213, v216, s[52:53]
	v_or_b32_e32 v216, 16, v150
	v_sub_u32_e32 v216, v72, v216
	v_or_b32_e32 v217, v216, v214
	v_med3_i32 v216, v216, 0, v181
	v_lshl_add_u32 v216, v216, 4, v206
	ds_read_b32 v216, v216
	v_cmp_lt_i32_e64 s[54:55], -1, v217
	s_waitcnt lgkmcnt(0)
	v_add_f32_e32 v220, v28, v216
	v_max_f32_e32 v216, v213, v220
	v_cndmask_b32_e64 v213, v213, v216, s[54:55]
	v_or_b32_e32 v216, 17, v150
	v_sub_u32_e32 v216, v72, v216
	v_or_b32_e32 v217, v216, v214
	v_med3_i32 v216, v216, 0, v181
	v_lshl_add_u32 v216, v216, 4, v206
	ds_read_b32 v216, v216
	v_cmp_lt_i32_e64 s[56:57], -1, v217
	s_waitcnt lgkmcnt(0)
	v_add_f32_e32 v221, v29, v216
	v_max_f32_e32 v216, v213, v213
	v_max_f32_e32 v216, v216, v221
	v_cndmask_b32_e64 v213, v213, v216, s[56:57]
	v_or_b32_e32 v216, 18, v150
	v_sub_u32_e32 v216, v72, v216
	v_or_b32_e32 v217, v216, v214
	v_med3_i32 v216, v216, 0, v181
	v_lshl_add_u32 v216, v216, 4, v206
	v_or_b32_e32 v150, 19, v150
	ds_read_b32 v216, v216
	v_sub_u32_e32 v150, v72, v150
	v_or_b32_e32 v214, v150, v214
	v_med3_i32 v150, v150, 0, v181
	v_lshl_add_u32 v150, v150, 4, v206
	ds_read_b32 v150, v150
	s_waitcnt lgkmcnt(1)
	v_add_f32_e32 v222, v30, v216
	v_max_f32_e32 v216, v213, v213
	v_cmp_gt_i32_e64 s[58:59], 0, v217
	v_max_f32_e32 v216, v216, v222
	v_cmp_gt_i32_e64 s[60:61], 0, v214
	v_cndmask_b32_e64 v213, v216, v213, s[58:59]
	s_waitcnt lgkmcnt(0)
	v_add_f32_e32 v150, v31, v150
	v_max_f32_e32 v214, v213, v213
	v_max_f32_e32 v214, v214, v150
	v_cndmask_b32_e64 v213, v214, v213, s[60:61]
	v_mov_b32_e32 v214, v213
	s_nop 1
	v_permlane16_swap_b32_e32 v213, v214
	v_max_f32_e32 v213, v213, v214
	v_mov_b32_e32 v214, v213
	s_nop 1
	v_permlane32_swap_b32_e32 v213, v214
	v_max3_f32 v213, v144, v213, v214
	v_sub_f32_e32 v151, v151, v213
	v_mul_f32_e32 v151, 0x3fb8aa3b, v151
	v_exp_f32_e32 v151, v151
	v_sub_f32_e32 v150, v150, v213
	v_mul_f32_e32 v150, 0x3fb8aa3b, v150
	v_exp_f32_e32 v150, v150
	v_cndmask_b32_e32 v216, 0, v151, vcc
	v_sub_f32_e32 v151, v215, v213
	v_mul_f32_e32 v151, 0x3fb8aa3b, v151
	v_exp_f32_e32 v151, v151
	v_cndmask_b32_e64 v223, v150, 0, s[60:61]
	v_add_f32_e32 v150, 0, v216
	v_cndmask_b32_e64 v217, 0, v151, s[48:49]
	v_sub_f32_e32 v151, v218, v213
	v_mul_f32_e32 v151, 0x3fb8aa3b, v151
	v_exp_f32_e32 v151, v151
	v_add_f32_e32 v150, v217, v150
	s_mov_b64 s[48:49], 0
	v_cndmask_b32_e64 v218, 0, v151, s[50:51]
	v_sub_f32_e32 v151, v219, v213
	v_mul_f32_e32 v151, 0x3fb8aa3b, v151
	v_exp_f32_e32 v151, v151
	v_add_f32_e32 v150, v218, v150
	v_cndmask_b32_e64 v219, 0, v151, s[52:53]
	v_sub_f32_e32 v151, v220, v213
	v_mul_f32_e32 v151, 0x3fb8aa3b, v151
	v_exp_f32_e32 v151, v151
	v_add_f32_e32 v150, v219, v150
	v_cndmask_b32_e64 v220, 0, v151, s[54:55]
	v_sub_f32_e32 v151, v221, v213
	v_mul_f32_e32 v151, 0x3fb8aa3b, v151
	v_exp_f32_e32 v151, v151
	v_add_f32_e32 v150, v220, v150
	v_cndmask_b32_e64 v221, 0, v151, s[56:57]
	v_sub_f32_e32 v151, v222, v213
	v_mul_f32_e32 v151, 0x3fb8aa3b, v151
	v_exp_f32_e32 v151, v151
	v_add_f32_e32 v150, v221, v150
	v_cndmask_b32_e64 v222, v151, 0, s[58:59]
	v_add_f32_e32 v150, v222, v150
	v_add_f32_e32 v215, v223, v150
; #define LAS __attribute__((address_space(3)))
; __device__ __forceinline__ float fexp(float x) { return __expf(x); }
; __device__ __forceinline__ void softmax_half_far(f32x4 (&acc)[2], const LAS float* lutg, SmState& st, f32x4 (&O)[4]) {
;     const float bias = lutg[1023 * 4];
;     float mx = -1e30f;
; #pragma unroll
;     for (int nt = 0; nt < 2; ++nt)
; #pragma unroll
;         for (int i = 0; i < 4; ++i) { const float lg = acc[nt][i] + bias; acc[nt][i] = lg; mx = fmaxf(mx, lg); }
;     mx = fmaxf(mx, __shfl_xor(mx, 16)); mx = fmaxf(mx, __shfl_xor(mx, 32));
;     const float mn = fmaxf(st.m, mx);
;     const float sc = fexp(st.m - mn);
;     float ls = 0.f;
; #pragma unroll
;     for (int nt = 0; nt < 2; ++nt)
; #pragma unroll
;         for (int i = 0; i < 4; ++i) { const float p = fexp(acc[nt][i] - mn); acc[nt][i] = p; ls += p; }
;     st.l = st.l * sc + ls; st.m = mn;
; #pragma unroll
;     for (int dt = 0; dt < 4; ++dt) O[dt] = O[dt] * sc;
; }
; __device__ __forceinline__ void nsa_wave(CArgs* Ap, int l, int b, int g, int tq0, const LAS float* lut, LAS float* imp, int lane) {
;     ...
;             const long p8 = p_to_fp8(acc);
; #pragma unroll
;             for (int q2 = 0; q2 < 4; ++q2) { const long pm = (qi == q2) ? p8 : 0l; pv_acch8(Od, vq[q2], pm); }
;             if (more) {
; #pragma unroll
;                 for (int q2 = 0; q2 < 4; ++q2) load_vh8(vq[q2], Vs8 + (size_t)jn[q2] * 4096, h1, lane); }
.Lsla_1273:
	s_andn2_b64 vcc, exec, s[48:49]
	s_cbranch_vccnz .Lsla_1275
	v_add_f32_e32 v24, v24, v228
	v_add_f32_e32 v25, v25, v228
	v_add_f32_e32 v26, v26, v228
	v_add_f32_e32 v27, v27, v228
	v_max3_f32 v151, v24, s74, v25
	v_add_f32_e32 v28, v28, v228
	v_max3_f32 v151, v151, v26, v27
	v_add_f32_e32 v29, v29, v228
	v_max3_f32 v151, v151, v28, v29
	v_add_f32_e32 v30, v30, v228
	v_add_f32_e32 v31, v31, v228
	v_max3_f32 v150, v151, v30, v31
	v_mov_b32_e32 v151, v150
	s_nop 1
	v_permlane16_swap_b32_e32 v150, v151
	v_max_f32_e32 v150, v150, v151
	v_mov_b32_e32 v151, v150
	s_nop 1
	v_permlane32_swap_b32_e32 v150, v151
	v_max3_f32 v213, v144, v150, v151
	v_sub_f32_e32 v25, v25, v213
	v_sub_f32_e32 v24, v24, v213
	v_mul_f32_e32 v25, 0x3fb8aa3b, v25
	v_mul_f32_e32 v24, 0x3fb8aa3b, v24
	v_exp_f32_e32 v217, v25
	v_sub_f32_e32 v25, v28, v213
	v_sub_f32_e32 v26, v26, v213
	v_exp_f32_e32 v216, v24
	v_mul_f32_e32 v25, 0x3fb8aa3b, v25
	v_mul_f32_e32 v26, 0x3fb8aa3b, v26
	v_sub_f32_e32 v24, v27, v213
	v_exp_f32_e32 v220, v25
	v_sub_f32_e32 v25, v29, v213
	v_exp_f32_e32 v218, v26
	v_mul_f32_e32 v24, 0x3fb8aa3b, v24
	v_mul_f32_e32 v25, 0x3fb8aa3b, v25
	v_exp_f32_e32 v219, v24
	v_exp_f32_e32 v221, v25
	v_sub_f32_e32 v25, v30, v213
	v_add_f32_e32 v24, 0, v216
	v_mul_f32_e32 v25, 0x3fb8aa3b, v25
	v_add_f32_e32 v24, v217, v24
	v_exp_f32_e32 v222, v25
	v_sub_f32_e32 v25, v31, v213
	v_add_f32_e32 v24, v218, v24
	v_mul_f32_e32 v25, 0x3fb8aa3b, v25
	v_add_f32_e32 v24, v219, v24
	v_exp_f32_e32 v223, v25
	v_add_f32_e32 v24, v220, v24
	v_add_f32_e32 v24, v221, v24
	v_add_f32_e32 v24, v222, v24
	v_add_f32_e32 v215, v223, v24
.Lsla_1275:
	v_sub_f32_e32 v24, v144, v213
	v_mul_f32_e32 v25, 0x43800000, v216
	v_mul_f32_e32 v26, 0x43800000, v217
	v_mul_f32_e32 v29, 0x43800000, v220
	v_mul_f32_e32 v30, 0x43800000, v221
	v_mov_b32_e32 v31, 0
	v_mov_b32_e32 v144, 0
	v_cvt_pk_fp8_f32 v144, v29, v30
	v_cvt_pk_fp8_f32 v31, v25, v26
	v_mul_f32_e32 v24, 0x3fb8aa3b, v24
	v_mul_f32_e32 v27, 0x43800000, v218
	v_mul_f32_e32 v28, 0x43800000, v219
	v_mul_f32_e32 v25, 0x43800000, v222
	v_mul_f32_e32 v26, 0x43800000, v223
	v_exp_f32_e32 v24, v24
	v_cvt_pk_fp8_f32 v144, v25, v26 op_sel:[0,0,1]
	v_cvt_pk_fp8_f32 v31, v27, v28 op_sel:[0,0,1]
	s_and_b64 vcc, exec, s[46:47]
	v_pk_mul_f32 v[22:23], v[22:23], v[24:25] op_sel_hi:[1,0]
	v_pk_mul_f32 v[20:21], v[20:21], v[24:25] op_sel_hi:[1,0]
	v_cndmask_b32_e64 v27, 0, v144, s[6:7]
	v_cndmask_b32_e64 v26, 0, v31, s[6:7]
	v_pk_mul_f32 v[18:19], v[18:19], v[24:25] op_sel_hi:[1,0]
	v_pk_mul_f32 v[16:17], v[16:17], v[24:25] op_sel_hi:[1,0]
	v_pk_mul_f32 v[14:15], v[14:15], v[24:25] op_sel_hi:[1,0]
	v_pk_mul_f32 v[12:13], v[12:13], v[24:25] op_sel_hi:[1,0]
	v_pk_mul_f32 v[10:11], v[10:11], v[24:25] op_sel_hi:[1,0]
	v_pk_mul_f32 v[8:9], v[8:9], v[24:25] op_sel_hi:[1,0]
	s_waitcnt vmcnt(31)
	s_nop 0
	v_mfma_f32_16x16x32_fp8_fp8 v[20:23], v[40:41], v[26:27], v[20:23]
	v_mfma_f32_16x16x32_fp8_fp8 v[16:19], v[42:43], v[26:27], v[16:19]
	s_waitcnt vmcnt(30)
	v_mfma_f32_16x16x32_fp8_fp8 v[12:15], v[44:45], v[26:27], v[12:15]
	v_mfma_f32_16x16x32_fp8_fp8 v[8:11], v[46:47], v[26:27], v[8:11]
	v_cndmask_b32_e64 v27, 0, v144, s[8:9]
	v_cndmask_b32_e64 v26, 0, v31, s[8:9]
	s_waitcnt vmcnt(29)
	s_nop 0
	v_mfma_f32_16x16x32_fp8_fp8 v[20:23], v[56:57], v[26:27], v[20:23]
	v_mfma_f32_16x16x32_fp8_fp8 v[16:19], v[58:59], v[26:27], v[16:19]
	s_waitcnt vmcnt(28)
	v_mfma_f32_16x16x32_fp8_fp8 v[12:15], v[60:61], v[26:27], v[12:15]
	v_mfma_f32_16x16x32_fp8_fp8 v[8:11], v[62:63], v[26:27], v[8:11]
	v_cndmask_b32_e64 v27, 0, v144, s[10:11]
	v_cndmask_b32_e64 v26, 0, v31, s[10:11]
	s_waitcnt vmcnt(27)
	s_nop 0
	v_mfma_f32_16x16x32_fp8_fp8 v[20:23], v[74:75], v[26:27], v[20:23]
	v_mfma_f32_16x16x32_fp8_fp8 v[16:19], v[76:77], v[26:27], v[16:19]
	s_waitcnt vmcnt(26)
	v_mfma_f32_16x16x32_fp8_fp8 v[12:15], v[78:79], v[26:27], v[12:15]
	v_mfma_f32_16x16x32_fp8_fp8 v[8:11], v[80:81], v[26:27], v[8:11]
	v_cndmask_b32_e64 v27, 0, v144, s[12:13]
	v_cndmask_b32_e64 v26, 0, v31, s[12:13]
	s_waitcnt vmcnt(25)
	s_nop 0
	v_mfma_f32_16x16x32_fp8_fp8 v[20:23], v[106:107], v[26:27], v[20:23]
	v_mfma_f32_16x16x32_fp8_fp8 v[16:19], v[108:109], v[26:27], v[16:19]
	s_waitcnt vmcnt(24)
	v_mfma_f32_16x16x32_fp8_fp8 v[12:15], v[122:123], v[26:27], v[12:15]
	v_mfma_f32_16x16x32_fp8_fp8 v[8:11], v[124:125], v[26:27], v[8:11]
	s_add_u32 s48, s0, s26
	s_addc_u32 s49, s1, s27
	global_load_dwordx4 v[40:43], v84, s[48:49]
	global_load_dwordx4 v[44:47], v84, s[48:49] offset:1024
	s_add_u32 s48, s0, s28
	s_addc_u32 s49, s1, s29
	global_load_dwordx4 v[56:59], v84, s[48:49]
	global_load_dwordx4 v[60:63], v84, s[48:49] offset:1024
	s_add_u32 s48, s0, s30
	s_addc_u32 s49, s1, s31
	global_load_dwordx4 v[74:77], v84, s[48:49]
	global_load_dwordx4 v[78:81], v84, s[48:49] offset:1024
	s_add_u32 s48, s0, s34
	s_addc_u32 s49, s1, s35
	global_load_dwordx4 v[106:109], v84, s[48:49]
	global_load_dwordx4 v[122:125], v84, s[48:49] offset:1024
	v_fmac_f32_e32 v215, v212, v24
	s_add_i32 s24, s24, 32
	s_nop 0
	v_mov_b32_e32 v212, v215
	v_mov_b32_e32 v144, v213
	s_waitcnt vmcnt(31)
	v_mfma_f32_16x16x32_fp8_fp8 v[24:27], v[184:185], v[82:83], 0
	v_mov_b32_e32 v214, v165
	s_nop 0
	s_waitcnt vmcnt(30)
	v_mfma_f32_16x16x32_fp8_fp8 v[28:31], v[188:189], v[82:83], 0
	s_nop 0
	s_nop 0
	v_mfma_f32_16x16x32_fp8_fp8 v[24:27], v[186:187], v[104:105], v[24:27]
	v_mfma_f32_16x16x32_fp8_fp8 v[28:31], v[190:191], v[104:105], v[28:31]
	s_waitcnt vmcnt(29)
	v_mfma_f32_16x16x32_fp8_fp8 v[24:27], v[192:193], v[98:99], v[24:27]
	s_waitcnt vmcnt(28)
; #define LAS __attribute__((address_space(3)))
; __device__ __forceinline__ float fexp(float x) { return __expf(x); }
; template <int MODE>
; __device__ __forceinline__ void softmax_half(f32x4 (&acc)[2], int base, bool ok, int t, int g4, const LAS float* lutg, SmState& st, f32x4 (&O)[4], bf16x8& pB) {
;     float mx = -1e30f; unsigned vm = 0u;
; #pragma unroll
;     for (int nt = 0; nt < 2; ++nt)
; #pragma unroll
;         for (int i = 0; i < 4; ++i) {
;             const int key = base + 16 * nt + 4 * g4 + i;
;             const int dist = t - key;
;             bool valid = dist >= 0;
;             if (MODE == 1) valid = valid && ok;
;             if (MODE == 2) valid = valid && dist < 512;
;             int dc = dist < 0 ? 0 : dist; dc = dc > 1023 ? 1023 : dc;
;             const float lg = acc[nt][i] + lutg[dc * 4];
;             acc[nt][i] = lg;
;             if (valid) { mx = fmaxf(mx, lg); vm |= 1u << (nt * 4 + i); }
;         }
;     mx = fmaxf(mx, __shfl_xor(mx, 16)); mx = fmaxf(mx, __shfl_xor(mx, 32));
;     const float mn = fmaxf(st.m, mx);
;     const float sc = fexp(st.m - mn);
;     float ls = 0.f;
; #pragma unroll
;     for (int nt = 0; nt < 2; ++nt)
; #pragma unroll
;         for (int i = 0; i < 4; ++i) { const float p = ((vm >> (nt * 4 + i)) & 1u) ? fexp(acc[nt][i] - mn) : 0.f; acc[nt][i] = p; ls += p; }
;     st.l = st.l * sc + ls; st.m = mn;
; __device__ __forceinline__ void nsa_wave(CArgs* Ap, int l, int b, int g, int tq0, const LAS float* lut, LAS float* imp, int lane) {
;     ...
;             for (int q2 = 0; q2 < 4; ++q2) { long qm[2]; qm[0] = (qi == q2) ? q8[0] : 0l; qm[1] = (qi == q2) ? q8[1] : 0l; qk_acch8(acc, kq[q2], qm); }
;             const bool more = hs + 1 < nh; const int s1 = (hs + 1) >> 1, h1 = (hs + 1) & 1;
;             int jn[4];
; #pragma unroll
;             for (int q2 = 0; q2 < 4; ++q2) { int j = more ? __builtin_amdgcn_readlane(selreg, 16 * q2 + s1) : 0; jn[q2] = j < 0 ? 0 : j; }
;             if (more) {
; #pragma unroll
;                 for (int q2 = 0; q2 < 4; ++q2) load_kh8(kq[q2], Ks8 + (size_t)jn[q2] * 4096, h1, lane); }
	v_mfma_f32_16x16x32_fp8_fp8 v[28:31], v[196:197], v[98:99], v[28:31]
	v_mfma_f32_16x16x32_fp8_fp8 v[24:27], v[194:195], v[110:111], v[24:27]
	v_mfma_f32_16x16x32_fp8_fp8 v[28:31], v[198:199], v[110:111], v[28:31]
	s_waitcnt vmcnt(27)
	v_mfma_f32_16x16x32_fp8_fp8 v[24:27], v[230:231], v[100:101], v[24:27]
	s_waitcnt vmcnt(26)
	v_mfma_f32_16x16x32_fp8_fp8 v[28:31], v[234:235], v[100:101], v[28:31]
	v_mfma_f32_16x16x32_fp8_fp8 v[24:27], v[232:233], v[120:121], v[24:27]
	v_mfma_f32_16x16x32_fp8_fp8 v[28:31], v[236:237], v[120:121], v[28:31]
	s_waitcnt vmcnt(25)
	v_mfma_f32_16x16x32_fp8_fp8 v[24:27], v[238:239], v[102:103], v[24:27]
	s_waitcnt vmcnt(24)
	v_mfma_f32_16x16x32_fp8_fp8 v[28:31], v[242:243], v[102:103], v[28:31]
	v_mfma_f32_16x16x32_fp8_fp8 v[24:27], v[240:241], v[126:127], v[24:27]
	v_mfma_f32_16x16x32_fp8_fp8 v[28:31], v[244:245], v[126:127], v[28:31]
	s_add_u32 s48, s96, s26
	s_addc_u32 s49, s97, s27
	global_load_dwordx4 v[184:187], v229, s[48:49]
	global_load_dwordx4 v[188:191], v229, s[48:49] offset:1024
	s_add_u32 s48, s96, s28
	s_addc_u32 s49, s97, s29
	global_load_dwordx4 v[192:195], v229, s[48:49]
	global_load_dwordx4 v[196:199], v229, s[48:49] offset:1024
	s_add_u32 s48, s96, s30
	s_addc_u32 s49, s97, s31
	global_load_dwordx4 v[230:233], v229, s[48:49]
	global_load_dwordx4 v[234:237], v229, s[48:49] offset:1024
	s_add_u32 s48, s96, s34
	s_addc_u32 s49, s97, s35
	global_load_dwordx4 v[238:241], v229, s[48:49]
	global_load_dwordx4 v[242:245], v229, s[48:49] offset:1024
.Lslb_1271:
	s_and_b32 s50, s24, 32
	s_waitcnt lgkmcnt(0)
	v_lshl_or_b32 v150, v214, 6, s50
	v_sub_u32_e32 v150, v211, v150
	v_cmp_lt_i32_e32 vcc, -1, v214
	v_cmp_lt_i32_e64 s[48:49], s75, v150
	s_and_b64 s[48:49], vcc, s[48:49]
	s_nop 0
	v_cndmask_b32_e64 v150, 0, 1, s[48:49]
	v_cmp_ne_u32_e32 vcc, 0, v150
	s_cmp_lg_u64 vcc, exec
	s_mov_b64 s[48:49], -1
	s_cbranch_scc0 .Lslb_1273
	v_max_i32_e32 v150, 0, v214
	v_lshlrev_b32_e32 v150, 6, v150
	v_or3_b32 v150, v150, s50, v88
	v_sub_u32_e32 v151, v72, v150
	v_or_b32_e32 v213, v151, v214
	v_med3_i32 v151, v151, 0, v181
	v_lshl_add_u32 v151, v151, 4, v206
	v_xad_u32 v215, v150, -1, v72
	ds_read_b32 v151, v151
	v_or_b32_e32 v216, v215, v214
	v_med3_i32 v215, v215, 0, v181
	v_lshl_add_u32 v215, v215, 4, v206
	ds_read_b32 v215, v215
	s_waitcnt lgkmcnt(1)
	v_add_f32_e32 v151, v24, v151
	v_cmp_lt_i32_e32 vcc, -1, v213
	v_max_f32_e32 v213, 0xf149f2ca, v151
	v_cmp_lt_i32_e64 s[48:49], -1, v216
	v_cndmask_b32_e32 v213, v182, v213, vcc
	s_waitcnt lgkmcnt(0)
	v_add_f32_e32 v215, v25, v215
	v_max_f32_e32 v216, v213, v215
	v_cndmask_b32_e64 v213, v213, v216, s[48:49]
	v_or_b32_e32 v216, 2, v150
	v_sub_u32_e32 v216, v72, v216
	v_or_b32_e32 v217, v216, v214
	v_med3_i32 v216, v216, 0, v181
	v_lshl_add_u32 v216, v216, 4, v206
	ds_read_b32 v216, v216
	v_cmp_lt_i32_e64 s[50:51], -1, v217
	s_waitcnt lgkmcnt(0)
	v_add_f32_e32 v218, v26, v216
	v_max_f32_e32 v216, v213, v218
	v_cndmask_b32_e64 v213, v213, v216, s[50:51]
	v_or_b32_e32 v216, 3, v150
	v_sub_u32_e32 v216, v72, v216
	v_or_b32_e32 v217, v216, v214
	v_med3_i32 v216, v216, 0, v181
	v_lshl_add_u32 v216, v216, 4, v206
	ds_read_b32 v216, v216
	v_cmp_lt_i32_e64 s[52:53], -1, v217
	s_waitcnt lgkmcnt(0)
	v_add_f32_e32 v219, v27, v216
	v_max_f32_e32 v216, v213, v219
	v_cndmask_b32_e64 v213, v213, v216, s[52:53]
	v_or_b32_e32 v216, 16, v150
	v_sub_u32_e32 v216, v72, v216
	v_or_b32_e32 v217, v216, v214
	v_med3_i32 v216, v216, 0, v181
	v_lshl_add_u32 v216, v216, 4, v206
	ds_read_b32 v216, v216
	v_cmp_lt_i32_e64 s[54:55], -1, v217
	s_waitcnt lgkmcnt(0)
	v_add_f32_e32 v220, v28, v216
	v_max_f32_e32 v216, v213, v220
	v_cndmask_b32_e64 v213, v213, v216, s[54:55]
	v_or_b32_e32 v216, 17, v150
	v_sub_u32_e32 v216, v72, v216
	v_or_b32_e32 v217, v216, v214
	v_med3_i32 v216, v216, 0, v181
	v_lshl_add_u32 v216, v216, 4, v206
	ds_read_b32 v216, v216
	v_cmp_lt_i32_e64 s[56:57], -1, v217
	s_waitcnt lgkmcnt(0)
	v_add_f32_e32 v221, v29, v216
	v_max_f32_e32 v216, v213, v213
	v_max_f32_e32 v216, v216, v221
	v_cndmask_b32_e64 v213, v213, v216, s[56:57]
	v_or_b32_e32 v216, 18, v150
	v_sub_u32_e32 v216, v72, v216
	v_or_b32_e32 v217, v216, v214
	v_med3_i32 v216, v216, 0, v181
	v_lshl_add_u32 v216, v216, 4, v206
	v_or_b32_e32 v150, 19, v150
	ds_read_b32 v216, v216
	v_sub_u32_e32 v150, v72, v150
	v_or_b32_e32 v214, v150, v214
	v_med3_i32 v150, v150, 0, v181
	v_lshl_add_u32 v150, v150, 4, v206
	ds_read_b32 v150, v150
	s_waitcnt lgkmcnt(1)
	v_add_f32_e32 v222, v30, v216
	v_max_f32_e32 v216, v213, v213
	v_cmp_gt_i32_e64 s[58:59], 0, v217
	v_max_f32_e32 v216, v216, v222
	v_cmp_gt_i32_e64 s[60:61], 0, v214
	v_cndmask_b32_e64 v213, v216, v213, s[58:59]
	s_waitcnt lgkmcnt(0)
	v_add_f32_e32 v150, v31, v150
	v_max_f32_e32 v214, v213, v213
	v_max_f32_e32 v214, v214, v150
	v_cndmask_b32_e64 v213, v214, v213, s[60:61]
	v_mov_b32_e32 v214, v213
	s_nop 1
	v_permlane16_swap_b32_e32 v213, v214
	v_max_f32_e32 v213, v213, v214
	v_mov_b32_e32 v214, v213
	s_nop 1
	v_permlane32_swap_b32_e32 v213, v214
	v_max3_f32 v213, v144, v213, v214
	v_sub_f32_e32 v151, v151, v213
	v_mul_f32_e32 v151, 0x3fb8aa3b, v151
	v_exp_f32_e32 v151, v151
	v_sub_f32_e32 v150, v150, v213
	v_mul_f32_e32 v150, 0x3fb8aa3b, v150
	v_exp_f32_e32 v150, v150
	v_cndmask_b32_e32 v216, 0, v151, vcc
	v_sub_f32_e32 v151, v215, v213
	v_mul_f32_e32 v151, 0x3fb8aa3b, v151
	v_exp_f32_e32 v151, v151
	v_cndmask_b32_e64 v223, v150, 0, s[60:61]
	v_add_f32_e32 v150, 0, v216
	v_cndmask_b32_e64 v217, 0, v151, s[48:49]
	v_sub_f32_e32 v151, v218, v213
	v_mul_f32_e32 v151, 0x3fb8aa3b, v151
	v_exp_f32_e32 v151, v151
	v_add_f32_e32 v150, v217, v150
	s_mov_b64 s[48:49], 0
	v_cndmask_b32_e64 v218, 0, v151, s[50:51]
	v_sub_f32_e32 v151, v219, v213
	v_mul_f32_e32 v151, 0x3fb8aa3b, v151
	v_exp_f32_e32 v151, v151
	v_add_f32_e32 v150, v218, v150
	v_cndmask_b32_e64 v219, 0, v151, s[52:53]
	v_sub_f32_e32 v151, v220, v213
	v_mul_f32_e32 v151, 0x3fb8aa3b, v151
	v_exp_f32_e32 v151, v151
	v_add_f32_e32 v150, v219, v150
	v_cndmask_b32_e64 v220, 0, v151, s[54:55]
	v_sub_f32_e32 v151, v221, v213
	v_mul_f32_e32 v151, 0x3fb8aa3b, v151
	v_exp_f32_e32 v151, v151
	v_add_f32_e32 v150, v220, v150
	v_cndmask_b32_e64 v221, 0, v151, s[56:57]
	v_sub_f32_e32 v151, v222, v213
	v_mul_f32_e32 v151, 0x3fb8aa3b, v151
	v_exp_f32_e32 v151, v151
	v_add_f32_e32 v150, v221, v150
	v_cndmask_b32_e64 v222, v151, 0, s[58:59]
	v_add_f32_e32 v150, v222, v150
	v_add_f32_e32 v215, v223, v150

; __device__ __forceinline__ void nsa_wave(CArgs* Ap, int l, int b, int g, int tq0, const LAS float* lut, LAS float* imp, int lane) {
;     ...
;             const long p8 = p_to_fp8(acc);
; #pragma unroll
;             for (int q2 = 0; q2 < 4; ++q2) { const long pm = (qi == q2) ? p8 : 0l; pv_acch8(Od, vq[q2], pm); }
;             if (more) {
; #pragma unroll
;                 for (int q2 = 0; q2 < 4; ++q2) load_vh8(vq[q2], Vs8 + (size_t)jn[q2] * 4096, h1, lane); }
;         }
.Lslb_1275:
	v_sub_f32_e32 v24, v144, v213
	v_mul_f32_e32 v25, 0x43800000, v216
	v_mul_f32_e32 v26, 0x43800000, v217
	v_mul_f32_e32 v29, 0x43800000, v220
	v_mul_f32_e32 v30, 0x43800000, v221
	v_mov_b32_e32 v31, 0
	v_mov_b32_e32 v144, 0
	v_cvt_pk_fp8_f32 v144, v29, v30
	v_cvt_pk_fp8_f32 v31, v25, v26
	v_mul_f32_e32 v24, 0x3fb8aa3b, v24
	v_mul_f32_e32 v27, 0x43800000, v218
	v_mul_f32_e32 v28, 0x43800000, v219
	v_mul_f32_e32 v25, 0x43800000, v222
	v_mul_f32_e32 v26, 0x43800000, v223
	v_exp_f32_e32 v24, v24
	v_cvt_pk_fp8_f32 v144, v25, v26 op_sel:[0,0,1]
	v_cvt_pk_fp8_f32 v31, v27, v28 op_sel:[0,0,1]
	s_and_b64 vcc, exec, s[46:47]
	v_pk_mul_f32 v[22:23], v[22:23], v[24:25] op_sel_hi:[1,0]
	v_pk_mul_f32 v[20:21], v[20:21], v[24:25] op_sel_hi:[1,0]
	v_cndmask_b32_e64 v27, 0, v144, s[6:7]
	v_cndmask_b32_e64 v26, 0, v31, s[6:7]
	v_pk_mul_f32 v[18:19], v[18:19], v[24:25] op_sel_hi:[1,0]
	v_pk_mul_f32 v[16:17], v[16:17], v[24:25] op_sel_hi:[1,0]
	v_pk_mul_f32 v[14:15], v[14:15], v[24:25] op_sel_hi:[1,0]
	v_pk_mul_f32 v[12:13], v[12:13], v[24:25] op_sel_hi:[1,0]
	v_pk_mul_f32 v[10:11], v[10:11], v[24:25] op_sel_hi:[1,0]
	v_pk_mul_f32 v[8:9], v[8:9], v[24:25] op_sel_hi:[1,0]
	s_waitcnt vmcnt(31)
	s_nop 0
	v_mfma_f32_16x16x32_fp8_fp8 v[20:23], v[134:135], v[26:27], v[20:23]
	v_mfma_f32_16x16x32_fp8_fp8 v[16:19], v[136:137], v[26:27], v[16:19]
	s_waitcnt vmcnt(30)
	v_mfma_f32_16x16x32_fp8_fp8 v[12:15], v[138:139], v[26:27], v[12:15]
	v_mfma_f32_16x16x32_fp8_fp8 v[8:11], v[140:141], v[26:27], v[8:11]
	v_cndmask_b32_e64 v27, 0, v144, s[8:9]
	v_cndmask_b32_e64 v26, 0, v31, s[8:9]
	s_waitcnt vmcnt(29)
	s_nop 0
	v_mfma_f32_16x16x32_fp8_fp8 v[20:23], v[152:153], v[26:27], v[20:23]
	v_mfma_f32_16x16x32_fp8_fp8 v[16:19], v[154:155], v[26:27], v[16:19]
	s_waitcnt vmcnt(28)
	v_mfma_f32_16x16x32_fp8_fp8 v[12:15], v[156:157], v[26:27], v[12:15]
	v_mfma_f32_16x16x32_fp8_fp8 v[8:11], v[158:159], v[26:27], v[8:11]
	v_cndmask_b32_e64 v27, 0, v144, s[10:11]
	v_cndmask_b32_e64 v26, 0, v31, s[10:11]
	s_waitcnt vmcnt(27)
	s_nop 0
	v_mfma_f32_16x16x32_fp8_fp8 v[20:23], v[160:161], v[26:27], v[20:23]
	v_mfma_f32_16x16x32_fp8_fp8 v[16:19], v[162:163], v[26:27], v[16:19]
	s_waitcnt vmcnt(26)
	v_mfma_f32_16x16x32_fp8_fp8 v[12:15], v[246:247], v[26:27], v[12:15]
	v_mfma_f32_16x16x32_fp8_fp8 v[8:11], v[248:249], v[26:27], v[8:11]
	v_cndmask_b32_e64 v27, 0, v144, s[12:13]
	v_cndmask_b32_e64 v26, 0, v31, s[12:13]
	s_waitcnt vmcnt(25)
	s_nop 0
	v_mfma_f32_16x16x32_fp8_fp8 v[20:23], v[0:1], v[26:27], v[20:23]
	v_mfma_f32_16x16x32_fp8_fp8 v[16:19], v[2:3], v[26:27], v[16:19]
	s_waitcnt vmcnt(24)
	v_mfma_f32_16x16x32_fp8_fp8 v[12:15], v[4:5], v[26:27], v[12:15]
	v_mfma_f32_16x16x32_fp8_fp8 v[8:11], v[6:7], v[26:27], v[8:11]
	s_add_u32 s48, s0, s26
	s_addc_u32 s49, s1, s27
	global_load_dwordx4 v[134:137], v229, s[48:49]
	global_load_dwordx4 v[138:141], v229, s[48:49] offset:1024
	s_add_u32 s48, s0, s28
	s_addc_u32 s49, s1, s29
	global_load_dwordx4 v[152:155], v229, s[48:49]
	global_load_dwordx4 v[156:159], v229, s[48:49] offset:1024
	s_add_u32 s48, s0, s30
	s_addc_u32 s49, s1, s31
	global_load_dwordx4 v[160:163], v229, s[48:49]
	global_load_dwordx4 v[246:249], v229, s[48:49] offset:1024
	s_add_u32 s48, s0, s34
	s_addc_u32 s49, s1, s35
	global_load_dwordx4 v[0:3], v229, s[48:49]
	global_load_dwordx4 v[4:7], v229, s[48:49] offset:1024
	v_fmac_f32_e32 v215, v212, v24
	s_add_i32 s24, s24, 32
	s_nop 0
	v_mov_b32_e32 v212, v215
	v_mov_b32_e32 v144, v213
	s_add_i32 s32, s32, 1
	s_mov_b64 s[36:37], s[26:27]
	s_mov_b64 s[38:39], s[28:29]
	s_mov_b64 s[40:41], s[30:31]
	s_mov_b64 s[84:85], s[34:35]
	s_add_i32 s25, s32, 1
	s_cmp_lt_i32 s25, s42
	s_cbranch_scc1 .Lsl_steady
.Lsl_last:
	s_waitcnt vmcnt(31)
	v_mfma_f32_16x16x32_fp8_fp8 v[24:27], v[32:33], v[82:83], 0
	v_add_u32_e32 v150, s32, v201
	v_and_or_b32 v150, v150, 63, v73
	s_waitcnt vmcnt(30)
	v_mfma_f32_16x16x32_fp8_fp8 v[28:31], v[36:37], v[82:83], 0
	v_lshlrev_b32_e32 v150, 2, v150
	ds_bpermute_b32 v214, v150, v210
	v_mfma_f32_16x16x32_fp8_fp8 v[24:27], v[34:35], v[104:105], v[24:27]
	v_mfma_f32_16x16x32_fp8_fp8 v[28:31], v[38:39], v[104:105], v[28:31]
	s_waitcnt vmcnt(29)
	v_mfma_f32_16x16x32_fp8_fp8 v[24:27], v[48:49], v[98:99], v[24:27]
	s_waitcnt vmcnt(28)
	v_mfma_f32_16x16x32_fp8_fp8 v[28:31], v[52:53], v[98:99], v[28:31]
	v_mfma_f32_16x16x32_fp8_fp8 v[24:27], v[50:51], v[110:111], v[24:27]
	v_mfma_f32_16x16x32_fp8_fp8 v[28:31], v[54:55], v[110:111], v[28:31]
	s_waitcnt vmcnt(27)
	v_mfma_f32_16x16x32_fp8_fp8 v[24:27], v[64:65], v[100:101], v[24:27]
	s_waitcnt vmcnt(26)
	v_mfma_f32_16x16x32_fp8_fp8 v[28:31], v[68:69], v[100:101], v[28:31]
	v_mfma_f32_16x16x32_fp8_fp8 v[24:27], v[66:67], v[120:121], v[24:27]
	v_mfma_f32_16x16x32_fp8_fp8 v[28:31], v[70:71], v[120:121], v[28:31]
	s_waitcnt vmcnt(25)
	v_mfma_f32_16x16x32_fp8_fp8 v[24:27], v[112:113], v[102:103], v[24:27]
	s_waitcnt vmcnt(24)
	v_mfma_f32_16x16x32_fp8_fp8 v[28:31], v[116:117], v[102:103], v[28:31]
	v_mfma_f32_16x16x32_fp8_fp8 v[24:27], v[114:115], v[126:127], v[24:27]
	v_mfma_f32_16x16x32_fp8_fp8 v[28:31], v[118:119], v[126:127], v[28:31]

; __device__ __forceinline__ void nsa_wave(CArgs* Ap, int l, int b, int g, int tq0, const LAS float* lut, LAS float* imp, int lane) {
;     ...
;             if (__all(jm >= 0 && t - (jm * 64 + 32 * hh + 31) >= 1023)) softmax_half_far(acc, lutg, st, Od);
;             else { bf16x8 pB; softmax_half<1>(acc, (jm < 0 ? 0 : jm) * 64 + 32 * hh, jm >= 0, t, g4, lutg, st, Od, pB); }
;             const long p8 = p_to_fp8(acc);
; #pragma unroll
;             for (int q2 = 0; q2 < 4; ++q2) { const long pm = (qi == q2) ? p8 : 0l; pv_acch8(Od, vq[q2], pm); }
;             if (more) {
; #pragma unroll
;                 for (int q2 = 0; q2 < 4; ++q2) load_vh8(vq[q2], Vs8 + (size_t)jn[q2] * 4096, h1, lane); }
;         }
.Lslc_1275:
	v_sub_f32_e32 v24, v144, v213
	v_mul_f32_e32 v25, 0x43800000, v216
	v_mul_f32_e32 v26, 0x43800000, v217
	v_mul_f32_e32 v29, 0x43800000, v220
	v_mul_f32_e32 v30, 0x43800000, v221
	v_mov_b32_e32 v31, 0
	v_mov_b32_e32 v144, 0
	v_cvt_pk_fp8_f32 v144, v29, v30
	v_cvt_pk_fp8_f32 v31, v25, v26
	v_mul_f32_e32 v24, 0x3fb8aa3b, v24
	v_mul_f32_e32 v27, 0x43800000, v218
	v_mul_f32_e32 v28, 0x43800000, v219
	v_mul_f32_e32 v25, 0x43800000, v222
	v_mul_f32_e32 v26, 0x43800000, v223
	v_exp_f32_e32 v24, v24
	v_cvt_pk_fp8_f32 v144, v25, v26 op_sel:[0,0,1]
	v_cvt_pk_fp8_f32 v31, v27, v28 op_sel:[0,0,1]
	s_and_b64 vcc, exec, s[46:47]
	v_pk_mul_f32 v[22:23], v[22:23], v[24:25] op_sel_hi:[1,0]
	v_pk_mul_f32 v[20:21], v[20:21], v[24:25] op_sel_hi:[1,0]
	v_cndmask_b32_e64 v27, 0, v144, s[6:7]
	v_cndmask_b32_e64 v26, 0, v31, s[6:7]
	v_pk_mul_f32 v[18:19], v[18:19], v[24:25] op_sel_hi:[1,0]
	v_pk_mul_f32 v[16:17], v[16:17], v[24:25] op_sel_hi:[1,0]
	v_pk_mul_f32 v[14:15], v[14:15], v[24:25] op_sel_hi:[1,0]
	v_pk_mul_f32 v[12:13], v[12:13], v[24:25] op_sel_hi:[1,0]
	v_pk_mul_f32 v[10:11], v[10:11], v[24:25] op_sel_hi:[1,0]
	v_pk_mul_f32 v[8:9], v[8:9], v[24:25] op_sel_hi:[1,0]
	s_waitcnt vmcnt(23)
	s_nop 0
	v_mfma_f32_16x16x32_fp8_fp8 v[20:23], v[40:41], v[26:27], v[20:23]
	v_mfma_f32_16x16x32_fp8_fp8 v[16:19], v[42:43], v[26:27], v[16:19]
	s_waitcnt vmcnt(22)
	v_mfma_f32_16x16x32_fp8_fp8 v[12:15], v[44:45], v[26:27], v[12:15]
	v_mfma_f32_16x16x32_fp8_fp8 v[8:11], v[46:47], v[26:27], v[8:11]
	v_cndmask_b32_e64 v27, 0, v144, s[8:9]
	v_cndmask_b32_e64 v26, 0, v31, s[8:9]
	s_waitcnt vmcnt(21)
	s_nop 0
	v_mfma_f32_16x16x32_fp8_fp8 v[20:23], v[56:57], v[26:27], v[20:23]
	v_mfma_f32_16x16x32_fp8_fp8 v[16:19], v[58:59], v[26:27], v[16:19]
	s_waitcnt vmcnt(20)
	v_mfma_f32_16x16x32_fp8_fp8 v[12:15], v[60:61], v[26:27], v[12:15]
	v_mfma_f32_16x16x32_fp8_fp8 v[8:11], v[62:63], v[26:27], v[8:11]
	v_cndmask_b32_e64 v27, 0, v144, s[10:11]
	v_cndmask_b32_e64 v26, 0, v31, s[10:11]
	s_waitcnt vmcnt(19)
	s_nop 0
	v_mfma_f32_16x16x32_fp8_fp8 v[20:23], v[74:75], v[26:27], v[20:23]
	v_mfma_f32_16x16x32_fp8_fp8 v[16:19], v[76:77], v[26:27], v[16:19]
	s_waitcnt vmcnt(18)
	v_mfma_f32_16x16x32_fp8_fp8 v[12:15], v[78:79], v[26:27], v[12:15]
	v_mfma_f32_16x16x32_fp8_fp8 v[8:11], v[80:81], v[26:27], v[8:11]
	v_cndmask_b32_e64 v27, 0, v144, s[12:13]
	v_cndmask_b32_e64 v26, 0, v31, s[12:13]
	s_waitcnt vmcnt(17)
	s_nop 0
	v_mfma_f32_16x16x32_fp8_fp8 v[20:23], v[106:107], v[26:27], v[20:23]
	v_mfma_f32_16x16x32_fp8_fp8 v[16:19], v[108:109], v[26:27], v[16:19]
	s_waitcnt vmcnt(16)
	v_mfma_f32_16x16x32_fp8_fp8 v[12:15], v[122:123], v[26:27], v[12:15]
	v_mfma_f32_16x16x32_fp8_fp8 v[8:11], v[124:125], v[26:27], v[8:11]
	v_fmac_f32_e32 v215, v212, v24
	s_add_i32 s24, s24, 32
	s_nop 0
	v_mov_b32_e32 v212, v215
	v_mov_b32_e32 v144, v213
	s_waitcnt vmcnt(15)
	v_mfma_f32_16x16x32_fp8_fp8 v[24:27], v[184:185], v[82:83], 0
	v_mov_b32_e32 v214, v165
	s_nop 0
	s_waitcnt vmcnt(14)
	v_mfma_f32_16x16x32_fp8_fp8 v[28:31], v[188:189], v[82:83], 0
	s_nop 0
	s_nop 0
	v_mfma_f32_16x16x32_fp8_fp8 v[24:27], v[186:187], v[104:105], v[24:27]
	v_mfma_f32_16x16x32_fp8_fp8 v[28:31], v[190:191], v[104:105], v[28:31]
	s_waitcnt vmcnt(13)
	v_mfma_f32_16x16x32_fp8_fp8 v[24:27], v[192:193], v[98:99], v[24:27]
	s_waitcnt vmcnt(12)
	v_mfma_f32_16x16x32_fp8_fp8 v[28:31], v[196:197], v[98:99], v[28:31]
	v_mfma_f32_16x16x32_fp8_fp8 v[24:27], v[194:195], v[110:111], v[24:27]
	v_mfma_f32_16x16x32_fp8_fp8 v[28:31], v[198:199], v[110:111], v[28:31]
	s_waitcnt vmcnt(11)
	v_mfma_f32_16x16x32_fp8_fp8 v[24:27], v[230:231], v[100:101], v[24:27]
	s_waitcnt vmcnt(10)
	v_mfma_f32_16x16x32_fp8_fp8 v[28:31], v[234:235], v[100:101], v[28:31]
	v_mfma_f32_16x16x32_fp8_fp8 v[24:27], v[232:233], v[120:121], v[24:27]
	v_mfma_f32_16x16x32_fp8_fp8 v[28:31], v[236:237], v[120:121], v[28:31]
	s_waitcnt vmcnt(9)
	v_mfma_f32_16x16x32_fp8_fp8 v[24:27], v[238:239], v[102:103], v[24:27]
	s_waitcnt vmcnt(8)
	v_mfma_f32_16x16x32_fp8_fp8 v[28:31], v[242:243], v[102:103], v[28:31]
	v_mfma_f32_16x16x32_fp8_fp8 v[24:27], v[240:241], v[126:127], v[24:27]
	v_mfma_f32_16x16x32_fp8_fp8 v[28:31], v[244:245], v[126:127], v[28:31]

; __device__ __forceinline__ void nsa_wave(CArgs* Ap, int l, int b, int g, int tq0, const LAS float* lut, LAS float* imp, int lane) {
;     ...
;             const long p8 = p_to_fp8(acc);
; #pragma unroll
;             for (int q2 = 0; q2 < 4; ++q2) { const long pm = (qi == q2) ? p8 : 0l; pv_acch8(Od, vq[q2], pm); }
;             if (more) {
; #pragma unroll
;                 for (int q2 = 0; q2 < 4; ++q2) load_vh8(vq[q2], Vs8 + (size_t)jn[q2] * 4096, h1, lane); }
;         }
;         float lt = st.l; lt += __shfl_xor(lt, 16); lt += __shfl_xor(lt, 32);
.Lsld_1275:
	v_sub_f32_e32 v24, v144, v213
	v_mul_f32_e32 v25, 0x43800000, v216
	v_mul_f32_e32 v26, 0x43800000, v217
	v_mul_f32_e32 v29, 0x43800000, v220
	v_mul_f32_e32 v30, 0x43800000, v221
	v_mov_b32_e32 v31, 0
	v_mov_b32_e32 v144, 0
	v_cvt_pk_fp8_f32 v144, v29, v30
	v_cvt_pk_fp8_f32 v31, v25, v26
	v_mul_f32_e32 v24, 0x3fb8aa3b, v24
	v_mul_f32_e32 v27, 0x43800000, v218
	v_mul_f32_e32 v28, 0x43800000, v219
	v_mul_f32_e32 v25, 0x43800000, v222
	v_mul_f32_e32 v26, 0x43800000, v223
	v_exp_f32_e32 v24, v24
	v_cvt_pk_fp8_f32 v144, v25, v26 op_sel:[0,0,1]
	v_cvt_pk_fp8_f32 v31, v27, v28 op_sel:[0,0,1]
	s_and_b64 vcc, exec, s[46:47]
	v_pk_mul_f32 v[22:23], v[22:23], v[24:25] op_sel_hi:[1,0]
	v_pk_mul_f32 v[20:21], v[20:21], v[24:25] op_sel_hi:[1,0]
	v_cndmask_b32_e64 v27, 0, v144, s[6:7]
	v_cndmask_b32_e64 v26, 0, v31, s[6:7]
	v_pk_mul_f32 v[18:19], v[18:19], v[24:25] op_sel_hi:[1,0]
	v_pk_mul_f32 v[16:17], v[16:17], v[24:25] op_sel_hi:[1,0]
	v_pk_mul_f32 v[14:15], v[14:15], v[24:25] op_sel_hi:[1,0]
	v_pk_mul_f32 v[12:13], v[12:13], v[24:25] op_sel_hi:[1,0]
	v_pk_mul_f32 v[10:11], v[10:11], v[24:25] op_sel_hi:[1,0]
	v_pk_mul_f32 v[8:9], v[8:9], v[24:25] op_sel_hi:[1,0]
	s_waitcnt vmcnt(7)
	s_nop 0
	v_mfma_f32_16x16x32_fp8_fp8 v[20:23], v[134:135], v[26:27], v[20:23]
	v_mfma_f32_16x16x32_fp8_fp8 v[16:19], v[136:137], v[26:27], v[16:19]
	s_waitcnt vmcnt(6)
	v_mfma_f32_16x16x32_fp8_fp8 v[12:15], v[138:139], v[26:27], v[12:15]
	v_mfma_f32_16x16x32_fp8_fp8 v[8:11], v[140:141], v[26:27], v[8:11]
	v_cndmask_b32_e64 v27, 0, v144, s[8:9]
	v_cndmask_b32_e64 v26, 0, v31, s[8:9]
	s_waitcnt vmcnt(5)
	s_nop 0
	v_mfma_f32_16x16x32_fp8_fp8 v[20:23], v[152:153], v[26:27], v[20:23]
	v_mfma_f32_16x16x32_fp8_fp8 v[16:19], v[154:155], v[26:27], v[16:19]
	s_waitcnt vmcnt(4)
	v_mfma_f32_16x16x32_fp8_fp8 v[12:15], v[156:157], v[26:27], v[12:15]
	v_mfma_f32_16x16x32_fp8_fp8 v[8:11], v[158:159], v[26:27], v[8:11]
	v_cndmask_b32_e64 v27, 0, v144, s[10:11]
	v_cndmask_b32_e64 v26, 0, v31, s[10:11]
	s_waitcnt vmcnt(3)
	s_nop 0
	v_mfma_f32_16x16x32_fp8_fp8 v[20:23], v[160:161], v[26:27], v[20:23]
	v_mfma_f32_16x16x32_fp8_fp8 v[16:19], v[162:163], v[26:27], v[16:19]
	s_waitcnt vmcnt(2)
	v_mfma_f32_16x16x32_fp8_fp8 v[12:15], v[246:247], v[26:27], v[12:15]
	v_mfma_f32_16x16x32_fp8_fp8 v[8:11], v[248:249], v[26:27], v[8:11]
	v_cndmask_b32_e64 v27, 0, v144, s[12:13]
	v_cndmask_b32_e64 v26, 0, v31, s[12:13]
	s_waitcnt vmcnt(1)
	s_nop 0
	v_mfma_f32_16x16x32_fp8_fp8 v[20:23], v[0:1], v[26:27], v[20:23]
	v_mfma_f32_16x16x32_fp8_fp8 v[16:19], v[2:3], v[26:27], v[16:19]
	s_waitcnt vmcnt(0)
	v_mfma_f32_16x16x32_fp8_fp8 v[12:15], v[4:5], v[26:27], v[12:15]
	v_mfma_f32_16x16x32_fp8_fp8 v[8:11], v[6:7], v[26:27], v[8:11]
	v_fmac_f32_e32 v215, v212, v24
	s_add_i32 s24, s24, 32
	s_nop 0
	v_mov_b32_e32 v212, v215
	v_mov_b32_e32 v144, v213
	s_nop 7
	ds_read_b128 v[0:3], v93 offset:4096
	ds_read_b128 v[4:7], v93 offset:5120
	s_branch .LBB0_1280
